# scoring: odd passes reuse the key fragments already in registers (same key side); LN1 and PEER-epilogue cross-lane sums by DPP instead of ds_bpermute
# speedup vs baseline: 1.1933x; 1.0017x over previous
.LBB0_696:
	v_add_u32_e32 v2, s48, v28
	v_cmp_gt_i32_e32 vcc, s52, v2
	v_mov_b32_e32 v3, s49
	v_mov_b32_e32 v4, s50
	v_cndmask_b32_e32 v3, v3, v4, vcc
	v_add_u32_e32 v26, v2, v3
	v_ashrrev_i32_e32 v27, 31, v26
	v_lshlrev_b64 v[2:3], 12, v[26:27]
	v_lshl_add_u64 v[68:69], v[18:19], 0, v[2:3]
	global_load_dwordx4 v[2:5], v[68:69], off offset:16
	global_load_dwordx4 v[6:9], v[68:69], off
	global_load_dwordx4 v[10:13], v[22:23], off offset:16
	global_load_dwordx4 v[14:17], v[22:23], off
	global_load_dwordx4 v[36:39], v[24:25], off offset:16
	global_load_dwordx4 v[40:43], v[24:25], off
	global_load_dwordx4 v[44:47], v[68:69], off offset:2064
	global_load_dwordx4 v[48:51], v[68:69], off offset:2048
	global_load_dwordx4 v[52:55], v[22:23], off offset:2064
	global_load_dwordx4 v[56:59], v[22:23], off offset:2048
	global_load_dwordx4 v[60:63], v[24:25], off offset:2064
	global_load_dwordx4 v[64:67], v[24:25], off offset:2048
	v_add_u32_e32 v28, s97, v28
	s_waitcnt vmcnt(10)
	v_add_f32_e32 v35, 0, v6
	v_add_f32_e32 v35, v35, v7
	v_add_f32_e32 v35, v35, v8
	v_add_f32_e32 v35, v35, v9
	v_add_f32_e32 v35, v35, v2
	v_add_f32_e32 v35, v35, v3
	v_add_f32_e32 v35, v35, v4
	v_add_f32_e32 v35, v35, v5
	s_waitcnt vmcnt(4)
	v_add_f32_e32 v35, v35, v48
	v_add_f32_e32 v35, v35, v49
	v_add_f32_e32 v35, v35, v50
	v_add_f32_e32 v35, v35, v51
	v_add_f32_e32 v35, v35, v44
	v_add_f32_e32 v35, v35, v45
	v_add_f32_e32 v35, v35, v46
	v_add_f32_e32 v35, v35, v47
	ds_bpermute_b32 v70, v29, v35
	s_waitcnt lgkmcnt(0)
	v_add_f32_e32 v35, v35, v70
	ds_bpermute_b32 v70, v30, v35
	s_waitcnt lgkmcnt(0)
	v_add_f32_e32 v35, v35, v70
	s_waitcnt lgkmcnt(0)
	s_nop 1
	v_add_f32_dpp v35, v35, v35 row_ror:8 row_mask:0xf bank_mask:0xf
	s_waitcnt lgkmcnt(0)
	s_nop 1
	v_mov_b32_dpp v70, v35 row_half_mirror row_mask:0xf bank_mask:0xf
	s_nop 1
	v_add_f32_dpp v35, v70, v35 quad_perm:[3,2,1,0] row_mask:0xf bank_mask:0xf
	s_waitcnt lgkmcnt(0)
	s_nop 1
	v_add_f32_dpp v35, v35, v35 quad_perm:[2,3,0,1] row_mask:0xf bank_mask:0xf
	s_waitcnt lgkmcnt(0)
	s_nop 1
	v_add_f32_dpp v35, v35, v35 quad_perm:[1,0,3,2] row_mask:0xf bank_mask:0xf
	v_mul_f32_e32 v70, 0x3a800000, v35
	v_pk_add_f32 v[6:7], v[6:7], v[70:71] op_sel_hi:[1,0] neg_lo:[0,1] neg_hi:[0,1]
	v_pk_add_f32 v[8:9], v[8:9], v[70:71] op_sel_hi:[1,0] neg_lo:[0,1] neg_hi:[0,1]
	v_pk_mul_f32 v[72:73], v[6:7], v[6:7]
	v_pk_mul_f32 v[74:75], v[8:9], v[8:9]
	v_add_f32_e32 v35, v72, v73
	v_pk_add_f32 v[76:77], v[2:3], v[70:71] op_sel_hi:[1,0] neg_lo:[0,1] neg_hi:[0,1]
	v_add_f32_e32 v35, v74, v35
	v_pk_mul_f32 v[2:3], v[76:77], v[76:77]
	v_add_f32_e32 v35, v75, v35
	v_pk_add_f32 v[78:79], v[4:5], v[70:71] op_sel_hi:[1,0] neg_lo:[0,1] neg_hi:[0,1]
	v_add_f32_e32 v2, v2, v35
	v_pk_mul_f32 v[4:5], v[78:79], v[78:79]
	v_add_f32_e32 v2, v3, v2
	v_pk_add_f32 v[48:49], v[48:49], v[70:71] op_sel_hi:[1,0] neg_lo:[0,1] neg_hi:[0,1]
	v_add_f32_e32 v2, v4, v2
	v_pk_mul_f32 v[80:81], v[48:49], v[48:49]
	v_add_f32_e32 v2, v5, v2
	v_pk_add_f32 v[50:51], v[50:51], v[70:71] op_sel_hi:[1,0] neg_lo:[0,1] neg_hi:[0,1]
	v_add_f32_e32 v2, v80, v2
	v_pk_mul_f32 v[82:83], v[50:51], v[50:51]
	v_add_f32_e32 v2, v81, v2
	v_pk_add_f32 v[44:45], v[44:45], v[70:71] op_sel_hi:[1,0] neg_lo:[0,1] neg_hi:[0,1]
	v_add_f32_e32 v2, v82, v2
	v_pk_mul_f32 v[84:85], v[44:45], v[44:45]
	v_add_f32_e32 v2, v83, v2
	v_pk_add_f32 v[46:47], v[46:47], v[70:71] op_sel_hi:[1,0] neg_lo:[0,1] neg_hi:[0,1]
	v_add_f32_e32 v2, v84, v2
	v_pk_mul_f32 v[70:71], v[46:47], v[46:47]
	v_add_f32_e32 v2, v85, v2
	v_add_f32_e32 v2, v70, v2
	v_add_f32_e32 v2, v71, v2
	ds_bpermute_b32 v3, v29, v2
	v_add_u32_e32 v35, 0xfffff000, v26
	v_lshrrev_b32_e32 v35, 10, v35
	v_add_u32_e32 v35, 1, v35
	s_waitcnt lgkmcnt(0)
	v_add_f32_e32 v2, v2, v3
	ds_bpermute_b32 v3, v30, v2
	s_waitcnt lgkmcnt(0)
	v_add_f32_e32 v2, v2, v3
	s_waitcnt lgkmcnt(0)
	s_nop 1
	v_add_f32_dpp v2, v2, v2 row_ror:8 row_mask:0xf bank_mask:0xf
	s_waitcnt lgkmcnt(0)
	s_nop 1
	v_mov_b32_dpp v3, v2 row_half_mirror row_mask:0xf bank_mask:0xf
	s_nop 1
	v_add_f32_dpp v2, v3, v2 quad_perm:[3,2,1,0] row_mask:0xf bank_mask:0xf
	s_waitcnt lgkmcnt(0)
	s_nop 1
	v_add_f32_dpp v2, v2, v2 quad_perm:[2,3,0,1] row_mask:0xf bank_mask:0xf
	s_waitcnt lgkmcnt(0)
	s_nop 1
	v_add_f32_dpp v2, v2, v2 quad_perm:[1,0,3,2] row_mask:0xf bank_mask:0xf
	v_fmamk_f32 v2, v2, 0x3a800000, v201
	v_cmp_gt_f32_e32 vcc, s62, v2
	v_mul_f32_e32 v3, 0x4b800000, v2
	s_nop 0
	v_cndmask_b32_e32 v2, v2, v3, vcc
	v_rsq_f32_e32 v2, v2
	s_nop 0
	v_mul_f32_e32 v3, 0x45800000, v2
	v_cndmask_b32_e32 v70, v2, v3, vcc
	v_cmp_lt_i32_e32 vcc, s57, v26
	v_pk_mul_f32 v[2:3], v[6:7], v[70:71] op_sel_hi:[1,0]
	v_pk_mul_f32 v[6:7], v[76:77], v[70:71] op_sel_hi:[1,0]
	v_cndmask_b32_e32 v35, 0, v35, vcc
	v_pk_fma_f32 v[2:3], v[14:15], v[2:3], v[40:41]
	v_pk_fma_f32 v[6:7], v[10:11], v[6:7], v[36:37]
	v_add_u32_e32 v35, s40, v35
	v_mov_b64_e32 v[36:37], s[74:75]
	v_pk_mul_f32 v[4:5], v[8:9], v[70:71] op_sel_hi:[1,0]
	v_mad_u64_u32 v[36:37], s[6:7], v35, s63, v[36:37]
	v_add_f32_e32 v35, 0, v2
	v_pk_fma_f32 v[4:5], v[16:17], v[4:5], v[42:43]
	v_add_f32_e32 v35, v3, v35
	v_add_f32_e32 v35, v4, v35
	v_add_f32_e32 v35, v5, v35
	v_pk_mul_f32 v[8:9], v[78:79], v[70:71] op_sel_hi:[1,0]
	v_add_f32_e32 v35, v6, v35
	v_pk_fma_f32 v[8:9], v[12:13], v[8:9], v[38:39]
	v_add_f32_e32 v35, v7, v35
	v_pk_mul_f32 v[10:11], v[48:49], v[70:71] op_sel_hi:[1,0]
	v_add_f32_e32 v35, v8, v35
	s_waitcnt vmcnt(0)
	v_pk_fma_f32 v[10:11], v[56:57], v[10:11], v[64:65]
	v_add_f32_e32 v35, v9, v35
	v_pk_mul_f32 v[12:13], v[50:51], v[70:71] op_sel_hi:[1,0]
	v_add_f32_e32 v35, v10, v35
	v_pk_fma_f32 v[12:13], v[58:59], v[12:13], v[66:67]
	v_add_f32_e32 v35, v11, v35
	v_pk_mul_f32 v[14:15], v[44:45], v[70:71] op_sel_hi:[1,0]
	v_add_f32_e32 v35, v12, v35
	v_pk_fma_f32 v[14:15], v[52:53], v[14:15], v[60:61]
	v_add_f32_e32 v35, v13, v35
	v_pk_mul_f32 v[16:17], v[46:47], v[70:71] op_sel_hi:[1,0]
	v_add_f32_e32 v35, v14, v35
	v_pk_fma_f32 v[16:17], v[54:55], v[16:17], v[62:63]
	v_add_f32_e32 v35, v15, v35
	v_add_f32_e32 v35, v16, v35
	v_add_f32_e32 v35, v17, v35
	ds_bpermute_b32 v38, v29, v35
	v_lshl_add_u64 v[52:53], v[36:37], 0, v[0:1]
	s_mov_b64 s[6:7], 0x18003000
	global_store_dwordx4 v[68:69], v[2:5], off
	global_store_dwordx4 v[68:69], v[6:9], off offset:16
	global_store_dwordx4 v[68:69], v[10:13], off offset:2048
	global_store_dwordx4 v[68:69], v[14:17], off offset:2064
	v_lshl_add_u64 v[54:55], v[52:53], 0, s[6:7]
	s_waitcnt lgkmcnt(0)
	v_add_f32_e32 v35, v35, v38
	ds_bpermute_b32 v38, v30, v35
	s_mov_b64 s[6:7], 0x18004000
	v_lshl_add_u64 v[58:59], v[52:53], 0, s[6:7]
	s_mov_b32 s6, 0x18004000
	v_lshlrev_b64 v[26:27], 11, v[26:27]
	s_waitcnt lgkmcnt(0)
	v_add_f32_e32 v35, v35, v38
	v_lshl_add_u64 v[26:27], v[20:21], 0, v[26:27]
	s_waitcnt lgkmcnt(0)
	s_nop 1
	v_add_f32_dpp v35, v35, v35 row_ror:8 row_mask:0xf bank_mask:0xf
	s_waitcnt lgkmcnt(0)
	s_nop 1
	v_mov_b32_dpp v38, v35 row_half_mirror row_mask:0xf bank_mask:0xf
	s_nop 1
	v_add_f32_dpp v35, v38, v35 quad_perm:[3,2,1,0] row_mask:0xf bank_mask:0xf
	s_waitcnt lgkmcnt(0)
	s_nop 1
	v_add_f32_dpp v35, v35, v35 quad_perm:[2,3,0,1] row_mask:0xf bank_mask:0xf
	s_waitcnt lgkmcnt(0)
	s_nop 1
	v_add_f32_dpp v35, v35, v35 quad_perm:[1,0,3,2] row_mask:0xf bank_mask:0xf
	global_load_dwordx4 v[36:39], v[54:55], off offset:2064
	global_load_dwordx4 v[40:43], v[54:55], off offset:2048
	global_load_dwordx4 v[44:47], v[58:59], off offset:2064
	global_load_dwordx4 v[48:51], v[58:59], off offset:2048
	v_mul_f32_e32 v56, 0x3a800000, v35
	v_pk_add_f32 v[62:63], v[14:15], v[56:57] op_sel_hi:[1,0] neg_lo:[0,1] neg_hi:[0,1]
	v_pk_add_f32 v[66:67], v[12:13], v[56:57] op_sel_hi:[1,0] neg_lo:[0,1] neg_hi:[0,1]
	v_pk_add_f32 v[72:73], v[10:11], v[56:57] op_sel_hi:[1,0] neg_lo:[0,1] neg_hi:[0,1]
	v_pk_add_f32 v[78:79], v[8:9], v[56:57] op_sel_hi:[1,0] neg_lo:[0,1] neg_hi:[0,1]
	v_pk_add_f32 v[2:3], v[2:3], v[56:57] op_sel_hi:[1,0] neg_lo:[0,1] neg_hi:[0,1]
	v_pk_add_f32 v[16:17], v[16:17], v[56:57] op_sel_hi:[1,0] neg_lo:[0,1] neg_hi:[0,1]
	v_pk_add_f32 v[6:7], v[6:7], v[56:57] op_sel_hi:[1,0] neg_lo:[0,1] neg_hi:[0,1]
	v_pk_add_f32 v[4:5], v[4:5], v[56:57] op_sel_hi:[1,0] neg_lo:[0,1] neg_hi:[0,1]
	v_pk_mul_f32 v[56:57], v[2:3], v[2:3]
	v_pk_mul_f32 v[82:83], v[4:5], v[4:5]
	v_add_f32_e32 v35, v56, v57
	v_add_f32_e32 v35, v82, v35
	v_add_f32_e32 v35, v83, v35
	v_pk_mul_f32 v[80:81], v[78:79], v[78:79]
	v_pk_mul_f32 v[74:75], v[72:73], v[72:73]
	v_pk_mul_f32 v[68:69], v[66:67], v[66:67]
	v_pk_mul_f32 v[64:65], v[62:63], v[62:63]
	v_pk_mul_f32 v[60:61], v[16:17], v[16:17]
	s_waitcnt vmcnt(1)
	v_pk_add_f32 v[44:45], v[44:45], 1.0 op_sel_hi:[1,0]
	s_waitcnt vmcnt(0)
	v_pk_add_f32 v[76:77], v[48:49], 1.0 op_sel_hi:[1,0]
	v_add_co_u32_e32 v48, vcc, s6, v52
	v_pk_add_f32 v[70:71], v[50:51], 1.0 op_sel_hi:[1,0]
	s_nop 0
	v_addc_co_u32_e32 v49, vcc, 0, v53, vcc
	global_load_dwordx4 v[8:11], v[48:49], off offset:-4096
	global_load_dwordx4 v[12:15], v[54:55], off offset:16
	s_nop 0
	global_load_dwordx4 v[48:51], v[48:49], off
	s_nop 0
	global_load_dwordx4 v[52:55], v[58:59], off offset:16
	v_pk_mul_f32 v[58:59], v[6:7], v[6:7]
	s_waitcnt vmcnt(1)
	v_pk_add_f32 v[48:49], v[48:49], 1.0 op_sel_hi:[1,0]
	v_add_f32_e32 v35, v58, v35
	v_add_f32_e32 v35, v59, v35
	v_add_f32_e32 v35, v80, v35
	v_add_f32_e32 v35, v81, v35
	v_add_f32_e32 v35, v74, v35
	v_add_f32_e32 v35, v75, v35
	v_add_f32_e32 v35, v68, v35
	v_add_f32_e32 v35, v69, v35
	v_add_f32_e32 v35, v64, v35
	v_add_f32_e32 v35, v65, v35
	v_add_f32_e32 v35, v60, v35
	v_add_f32_e32 v35, v61, v35
	ds_bpermute_b32 v56, v29, v35
	s_waitcnt vmcnt(0)
	v_pk_add_f32 v[54:55], v[54:55], 1.0 op_sel_hi:[1,0]
	v_pk_add_f32 v[52:53], v[52:53], 1.0 op_sel_hi:[1,0]
	v_pk_add_f32 v[50:51], v[50:51], 1.0 op_sel_hi:[1,0]
	s_waitcnt lgkmcnt(0)
	v_add_f32_e32 v35, v35, v56
	ds_bpermute_b32 v56, v30, v35
	s_waitcnt lgkmcnt(0)
	v_add_f32_e32 v35, v35, v56
	s_waitcnt lgkmcnt(0)
	s_nop 1
	v_add_f32_dpp v35, v35, v35 row_ror:8 row_mask:0xf bank_mask:0xf
	s_waitcnt lgkmcnt(0)
	s_nop 1
	v_mov_b32_dpp v56, v35 row_half_mirror row_mask:0xf bank_mask:0xf
	s_nop 1
	v_add_f32_dpp v35, v56, v35 quad_perm:[3,2,1,0] row_mask:0xf bank_mask:0xf
	s_waitcnt lgkmcnt(0)
	s_nop 1
	v_add_f32_dpp v35, v35, v35 quad_perm:[2,3,0,1] row_mask:0xf bank_mask:0xf
	s_waitcnt lgkmcnt(0)
	s_nop 1
	v_add_f32_dpp v35, v35, v35 quad_perm:[1,0,3,2] row_mask:0xf bank_mask:0xf
	v_fmamk_f32 v35, v35, 0x3a800000, v201
	v_cmp_gt_f32_e32 vcc, s62, v35
	v_mul_f32_e32 v56, 0x4b800000, v35
	s_nop 0
	v_cndmask_b32_e32 v35, v35, v56, vcc
	v_rsq_f32_e32 v35, v35
	s_nop 0
	v_mul_f32_e32 v56, 0x45800000, v35
	v_cndmask_b32_e32 v56, v35, v56, vcc
	v_pk_mul_f32 v[2:3], v[2:3], v[56:57] op_sel_hi:[1,0]
	v_pk_mul_f32 v[4:5], v[4:5], v[56:57] op_sel_hi:[1,0]
	v_pk_fma_f32 v[2:3], v[48:49], v[2:3], v[8:9]
	v_pk_mul_f32 v[8:9], v[78:79], v[56:57] op_sel_hi:[1,0]
	v_pk_mul_f32 v[6:7], v[6:7], v[56:57] op_sel_hi:[1,0]
	v_pk_fma_f32 v[8:9], v[54:55], v[8:9], v[14:15]
	v_pk_mul_f32 v[14:15], v[62:63], v[56:57] op_sel_hi:[1,0]
	v_pk_fma_f32 v[4:5], v[50:51], v[4:5], v[10:11]
	v_pk_fma_f32 v[6:7], v[52:53], v[6:7], v[12:13]
	v_pk_mul_f32 v[10:11], v[72:73], v[56:57] op_sel_hi:[1,0]
	v_pk_mul_f32 v[12:13], v[66:67], v[56:57] op_sel_hi:[1,0]
	v_pk_fma_f32 v[14:15], v[44:45], v[14:15], v[36:37]
	v_pk_mul_f32 v[16:17], v[16:17], v[56:57] op_sel_hi:[1,0]
	v_pk_add_f32 v[36:37], v[46:47], 1.0 op_sel_hi:[1,0]
	v_pk_fma_f32 v[10:11], v[76:77], v[10:11], v[40:41]
	v_pk_fma_f32 v[12:13], v[70:71], v[12:13], v[42:43]
	v_pk_fma_f32 v[16:17], v[36:37], v[16:17], v[38:39]
	v_cvt_pk_bf16_f32 v2, v2, v3
	v_cvt_pk_bf16_f32 v3, v4, v5
	v_cvt_pk_bf16_f32 v4, v6, v7
	v_cvt_pk_bf16_f32 v5, v8, v9
	v_cmp_lt_i32_e32 vcc, s64, v28
	global_store_dwordx4 v[26:27], v[2:5], off
	s_or_b64 s[4:5], vcc, s[4:5]
	s_nop 0
	v_cvt_pk_bf16_f32 v2, v10, v11
	v_cvt_pk_bf16_f32 v3, v12, v13
	v_cvt_pk_bf16_f32 v4, v14, v15
	v_cvt_pk_bf16_f32 v5, v16, v17
	global_store_dwordx4 v[26:27], v[2:5], off offset:1024
	s_andn2_b64 exec, exec, s[4:5]
	s_cbranch_execnz .LBB0_696

.LBB0_859:
	v_and_or_b32 v19, s19, 16, v137
	v_lshrrev_b32_e32 v18, 3, v19
	v_cmp_ne_u32_e32 vcc, 3, v18
	s_lshr_b32 s27, s26, 1
	s_lshl_b32 s20, s27, 6
	v_cndmask_b32_e32 v0, 2, v18, vcc
	v_mad_u64_u32 v[2:3], s[0:1], v0, s97, v[130:131]
	v_cmp_lt_i32_e32 vcc, s64, v2
	v_mov_b32_e32 v3, s50
	v_mov_b32_e32 v151, v1
	v_cndmask_b32_e32 v0, v2, v130, vcc
	v_add_u32_e32 v0, s48, v0
	v_cmp_gt_i32_e32 vcc, s52, v0
	v_mov_b32_e32 v2, s49
	s_movk_i32 s0, 0x2000
	v_cndmask_b32_e32 v2, v2, v3, vcc
	v_add_u32_e32 v2, v0, v2
	v_ashrrev_i32_e32 v3, 31, v2
	v_lshlrev_b64 v[2:3], 11, v[2:3]
	v_lshl_add_u64 v[2:3], v[132:133], 0, v[2:3]
	v_lshl_add_u64 v[2:3], s[20:21], 1, v[2:3]
	v_lshl_or_b32 v0, s27, 14, v197
	v_lshl_add_u64 v[2:3], v[2:3], 0, v[150:151]
	s_waitcnt lgkmcnt(7)
	v_lshl_add_u64 v[10:11], v[134:135], 0, v[0:1]
	global_load_dwordx4 v[6:9], v[2:3], off
	s_nop 0
	global_load_dwordx4 v[2:5], v[2:3], off offset:64
	s_waitcnt lgkmcnt(3)
	s_waitcnt lgkmcnt(0)
	v_cmp_gt_u32_e32 vcc, 24, v19
	s_and_b64 s[28:29], s[2:3], vcc
	s_bitcmp1_b32 s26, 0
	s_cbranch_scc0 .Lsc_load_keys
	s_waitcnt vmcnt(0)
	s_branch .Lsc_keys_ready
.Lsc_load_keys:
	s_mov_b64 s[98:99], 0x1000
	v_lshl_add_u64 v[104:105], v[10:11], 0, s[98:99]
	v_lshl_add_u64 v[106:107], v[104:105], 0, s[98:99]
	v_lshl_add_u64 v[108:109], v[106:107], 0, s[98:99]
	global_load_dwordx4 v[40:43], v[10:11], off
	global_load_dwordx4 v[44:47], v[10:11], off offset:64
	global_load_dwordx4 v[48:51], v[10:11], off offset:2048
	global_load_dwordx4 v[52:55], v[10:11], off offset:2112
	global_load_dwordx4 v[56:59], v[104:105], off
	global_load_dwordx4 v[60:63], v[104:105], off offset:64
	global_load_dwordx4 v[64:67], v[104:105], off offset:2048
	global_load_dwordx4 v[68:71], v[104:105], off offset:2112
	global_load_dwordx4 v[72:75], v[106:107], off
	global_load_dwordx4 v[76:79], v[106:107], off offset:64
	global_load_dwordx4 v[80:83], v[106:107], off offset:2048
	global_load_dwordx4 v[84:87], v[106:107], off offset:2112
	global_load_dwordx4 v[88:91], v[108:109], off
	global_load_dwordx4 v[92:95], v[108:109], off offset:64
	global_load_dwordx4 v[96:99], v[108:109], off offset:2048
	global_load_dwordx4 v[100:103], v[108:109], off offset:2112
.Lsc_keys_ready:
	s_waitcnt vmcnt(15)
	v_mfma_f32_16x16x32_bf16 v[110:113], v[40:43], v[6:9], 0
	s_waitcnt vmcnt(14)
	v_mfma_f32_16x16x32_bf16 v[110:113], v[44:47], v[2:5], v[110:113]
	s_waitcnt vmcnt(13)
	v_mfma_f32_16x16x32_bf16 v[114:117], v[48:51], v[6:9], 0
	s_waitcnt vmcnt(12)
	v_mfma_f32_16x16x32_bf16 v[114:117], v[52:55], v[2:5], v[114:117]
	s_nop 5
	v_and_or_b32 v38, v110, s65, v213
	v_and_or_b32 v39, v111, s65, v221
	v_and_or_b32 v20, v112, s65, v222
	v_and_or_b32 v19, v113, s65, v223
	v_mov_b32_e32 v22, v38
	v_max_f32_e32 v118, v22, v39
	v_min_f32_e32 v119, v22, v39
	v_max_f32_e32 v22, v118, v20
	v_med3_f32 v23, v118, v119, v20
	v_min_f32_e32 v24, v119, v20
	v_max_f32_e32 v118, v22, v19
	v_med3_f32 v119, v22, v23, v19
	v_med3_f32 v120, v23, v24, v19
	v_min_f32_e32 v121, v24, v19
	s_waitcnt vmcnt(11)
	v_mfma_f32_16x16x32_bf16 v[110:113], v[56:59], v[6:9], 0
	s_waitcnt vmcnt(10)
	v_mfma_f32_16x16x32_bf16 v[110:113], v[60:63], v[2:5], v[110:113]
	v_and_or_b32 v38, v114, s65, v224
	v_and_or_b32 v39, v115, s65, v225
	v_and_or_b32 v20, v116, s65, v226
	v_and_or_b32 v19, v117, s65, v227
	v_max_f32_e32 v22, v118, v38
	v_med3_f32 v23, v118, v119, v38
	v_med3_f32 v24, v119, v120, v38
	v_med3_f32 v25, v120, v121, v38
	v_min_f32_e32 v26, v121, v38
	v_max_f32_e32 v118, v22, v39
	v_med3_f32 v119, v22, v23, v39
	v_med3_f32 v120, v23, v24, v39
	v_med3_f32 v121, v24, v25, v39
	v_med3_f32 v122, v25, v26, v39
	v_min_f32_e32 v123, v26, v39
	v_max_f32_e32 v22, v118, v20
	v_med3_f32 v23, v118, v119, v20
	v_med3_f32 v24, v119, v120, v20
	v_med3_f32 v25, v120, v121, v20
	v_med3_f32 v26, v121, v122, v20
	v_med3_f32 v27, v122, v123, v20
	v_min_f32_e32 v28, v123, v20
	v_max_f32_e32 v118, v22, v19
	v_med3_f32 v119, v22, v23, v19
	v_med3_f32 v120, v23, v24, v19
	v_med3_f32 v121, v24, v25, v19
	v_med3_f32 v122, v25, v26, v19
	v_med3_f32 v123, v26, v27, v19
	v_med3_f32 v124, v27, v28, v19
	v_min_f32_e32 v125, v28, v19
	s_waitcnt vmcnt(9)
	v_mfma_f32_16x16x32_bf16 v[114:117], v[64:67], v[6:9], 0
	s_waitcnt vmcnt(8)
	v_mfma_f32_16x16x32_bf16 v[114:117], v[68:71], v[2:5], v[114:117]
	v_and_or_b32 v38, v110, s65, v228
	v_and_or_b32 v39, v111, s65, v229
	v_and_or_b32 v20, v112, s65, v230
	v_and_or_b32 v19, v113, s65, v231
	v_max_f32_e32 v22, v118, v38
	v_med3_f32 v23, v118, v119, v38
	v_med3_f32 v24, v119, v120, v38
	v_med3_f32 v25, v120, v121, v38
	v_med3_f32 v26, v121, v122, v38
	v_med3_f32 v27, v122, v123, v38
	v_med3_f32 v28, v123, v124, v38
	v_med3_f32 v29, v124, v125, v38
	v_min_f32_e32 v30, v125, v38
	v_max_f32_e32 v118, v22, v39
	v_med3_f32 v119, v22, v23, v39
	v_med3_f32 v120, v23, v24, v39
	v_med3_f32 v121, v24, v25, v39
	v_med3_f32 v122, v25, v26, v39
	v_med3_f32 v123, v26, v27, v39
	v_med3_f32 v124, v27, v28, v39
	v_med3_f32 v125, v28, v29, v39
	v_med3_f32 v126, v29, v30, v39
	v_min_f32_e32 v127, v30, v39
	v_max_f32_e32 v22, v118, v20
	v_med3_f32 v23, v118, v119, v20
	v_med3_f32 v24, v119, v120, v20
	v_med3_f32 v25, v120, v121, v20
	v_med3_f32 v26, v121, v122, v20
	v_med3_f32 v27, v122, v123, v20
	v_med3_f32 v28, v123, v124, v20
	v_med3_f32 v29, v124, v125, v20
	v_med3_f32 v30, v125, v126, v20
	v_med3_f32 v31, v126, v127, v20
	v_min_f32_e32 v32, v127, v20
	v_max_f32_e32 v118, v22, v19
	v_med3_f32 v119, v22, v23, v19
	v_med3_f32 v120, v23, v24, v19
	v_med3_f32 v121, v24, v25, v19
	v_med3_f32 v122, v25, v26, v19
	v_med3_f32 v123, v26, v27, v19
	v_med3_f32 v124, v27, v28, v19
	v_med3_f32 v125, v28, v29, v19
	v_med3_f32 v126, v29, v30, v19
	v_med3_f32 v127, v30, v31, v19
	v_med3_f32 v128, v31, v32, v19
	v_min_f32_e32 v129, v32, v19
	s_waitcnt vmcnt(7)
	v_mfma_f32_16x16x32_bf16 v[110:113], v[72:75], v[6:9], 0
	s_waitcnt vmcnt(6)
	v_mfma_f32_16x16x32_bf16 v[110:113], v[76:79], v[2:5], v[110:113]
	v_and_or_b32 v38, v114, s65, v232
	v_and_or_b32 v39, v115, s65, v233
	v_and_or_b32 v20, v116, s65, v234
	v_and_or_b32 v19, v117, s65, v235
	v_max_f32_e32 v22, v118, v38
	v_med3_f32 v23, v118, v119, v38
	v_med3_f32 v24, v119, v120, v38
	v_med3_f32 v25, v120, v121, v38
	v_med3_f32 v26, v121, v122, v38
	v_med3_f32 v27, v122, v123, v38
	v_med3_f32 v28, v123, v124, v38
	v_med3_f32 v29, v124, v125, v38
	v_med3_f32 v30, v125, v126, v38
	v_med3_f32 v31, v126, v127, v38
	v_med3_f32 v32, v127, v128, v38
	v_med3_f32 v33, v128, v129, v38
	v_min_f32_e32 v34, v129, v38
	v_max_f32_e32 v118, v22, v39
	v_med3_f32 v119, v22, v23, v39
	v_med3_f32 v120, v23, v24, v39
	v_med3_f32 v121, v24, v25, v39
	v_med3_f32 v122, v25, v26, v39
	v_med3_f32 v123, v26, v27, v39
	v_med3_f32 v124, v27, v28, v39
	v_med3_f32 v125, v28, v29, v39
	v_med3_f32 v126, v29, v30, v39
	v_med3_f32 v127, v30, v31, v39
	v_med3_f32 v128, v31, v32, v39
	v_med3_f32 v129, v32, v33, v39
	v_med3_f32 v10, v33, v34, v39
	v_min_f32_e32 v11, v34, v39
	v_max_f32_e32 v22, v118, v20
	v_med3_f32 v23, v118, v119, v20
	v_med3_f32 v24, v119, v120, v20
	v_med3_f32 v25, v120, v121, v20
	v_med3_f32 v26, v121, v122, v20
	v_med3_f32 v27, v122, v123, v20
	v_med3_f32 v28, v123, v124, v20
	v_med3_f32 v29, v124, v125, v20
	v_med3_f32 v30, v125, v126, v20
	v_med3_f32 v31, v126, v127, v20
	v_med3_f32 v32, v127, v128, v20
	v_med3_f32 v33, v128, v129, v20
	v_med3_f32 v34, v129, v10, v20
	v_med3_f32 v35, v10, v11, v20
	v_min_f32_e32 v36, v11, v20
	v_max_f32_e32 v118, v22, v19
	v_med3_f32 v119, v22, v23, v19
	v_med3_f32 v120, v23, v24, v19
	v_med3_f32 v121, v24, v25, v19
	v_med3_f32 v122, v25, v26, v19
	v_med3_f32 v123, v26, v27, v19
	v_med3_f32 v124, v27, v28, v19
	v_med3_f32 v125, v28, v29, v19
	v_med3_f32 v126, v29, v30, v19
	v_med3_f32 v127, v30, v31, v19
	v_med3_f32 v128, v31, v32, v19
	v_med3_f32 v129, v32, v33, v19
	v_med3_f32 v10, v33, v34, v19
	v_med3_f32 v11, v34, v35, v19
	v_med3_f32 v16, v35, v36, v19
	v_min_f32_e32 v17, v36, v19
	s_waitcnt vmcnt(5)
	v_mfma_f32_16x16x32_bf16 v[114:117], v[80:83], v[6:9], 0
	s_waitcnt vmcnt(4)
	v_mfma_f32_16x16x32_bf16 v[114:117], v[84:87], v[2:5], v[114:117]
	v_and_or_b32 v38, v110, s65, v236
	v_and_or_b32 v39, v111, s65, v237
	v_and_or_b32 v20, v112, s65, v238
	v_and_or_b32 v19, v113, s65, v239
	v_max_f32_e32 v22, v118, v38
	v_med3_f32 v23, v118, v119, v38
	v_med3_f32 v24, v119, v120, v38
	v_med3_f32 v25, v120, v121, v38
	v_med3_f32 v26, v121, v122, v38
	v_med3_f32 v27, v122, v123, v38
	v_med3_f32 v28, v123, v124, v38
	v_med3_f32 v29, v124, v125, v38
	v_med3_f32 v30, v125, v126, v38
	v_med3_f32 v31, v126, v127, v38
	v_med3_f32 v32, v127, v128, v38
	v_med3_f32 v33, v128, v129, v38
	v_med3_f32 v34, v129, v10, v38
	v_med3_f32 v35, v10, v11, v38
	v_med3_f32 v36, v11, v16, v38
	v_med3_f32 v37, v16, v17, v38
	v_max_f32_e32 v118, v22, v39
	v_med3_f32 v119, v22, v23, v39
	v_med3_f32 v120, v23, v24, v39
	v_med3_f32 v121, v24, v25, v39
	v_med3_f32 v122, v25, v26, v39
	v_med3_f32 v123, v26, v27, v39
	v_med3_f32 v124, v27, v28, v39
	v_med3_f32 v125, v28, v29, v39
	v_med3_f32 v126, v29, v30, v39
	v_med3_f32 v127, v30, v31, v39
	v_med3_f32 v128, v31, v32, v39
	v_med3_f32 v129, v32, v33, v39
	v_med3_f32 v10, v33, v34, v39
	v_med3_f32 v11, v34, v35, v39
	v_med3_f32 v16, v35, v36, v39
	v_med3_f32 v17, v36, v37, v39
	v_max_f32_e32 v22, v118, v20
	v_med3_f32 v23, v118, v119, v20
	v_med3_f32 v24, v119, v120, v20
	v_med3_f32 v25, v120, v121, v20
	v_med3_f32 v26, v121, v122, v20
	v_med3_f32 v27, v122, v123, v20
	v_med3_f32 v28, v123, v124, v20
	v_med3_f32 v29, v124, v125, v20
	v_med3_f32 v30, v125, v126, v20
	v_med3_f32 v31, v126, v127, v20
	v_med3_f32 v32, v127, v128, v20
	v_med3_f32 v33, v128, v129, v20
	v_med3_f32 v34, v129, v10, v20
	v_med3_f32 v35, v10, v11, v20
	v_med3_f32 v36, v11, v16, v20
	v_med3_f32 v37, v16, v17, v20
	v_max_f32_e32 v118, v22, v19
	v_med3_f32 v119, v22, v23, v19
	v_med3_f32 v120, v23, v24, v19
	v_med3_f32 v121, v24, v25, v19
	v_med3_f32 v122, v25, v26, v19
	v_med3_f32 v123, v26, v27, v19
	v_med3_f32 v124, v27, v28, v19
	v_med3_f32 v125, v28, v29, v19
	v_med3_f32 v126, v29, v30, v19
	v_med3_f32 v127, v30, v31, v19
	v_med3_f32 v128, v31, v32, v19
	v_med3_f32 v129, v32, v33, v19
	v_med3_f32 v10, v33, v34, v19
	v_med3_f32 v11, v34, v35, v19
	v_med3_f32 v16, v35, v36, v19
	v_med3_f32 v17, v36, v37, v19
	s_waitcnt vmcnt(3)
	v_mfma_f32_16x16x32_bf16 v[110:113], v[88:91], v[6:9], 0
	s_waitcnt vmcnt(2)
	v_mfma_f32_16x16x32_bf16 v[110:113], v[92:95], v[2:5], v[110:113]
	v_and_or_b32 v38, v114, s65, v240
	v_and_or_b32 v39, v115, s65, v241
	v_and_or_b32 v20, v116, s65, v242
	v_and_or_b32 v19, v117, s65, v243
	v_max_f32_e32 v22, v118, v38
	v_med3_f32 v23, v118, v119, v38
	v_med3_f32 v24, v119, v120, v38
	v_med3_f32 v25, v120, v121, v38
	v_med3_f32 v26, v121, v122, v38
	v_med3_f32 v27, v122, v123, v38
	v_med3_f32 v28, v123, v124, v38
	v_med3_f32 v29, v124, v125, v38
	v_med3_f32 v30, v125, v126, v38
	v_med3_f32 v31, v126, v127, v38
	v_med3_f32 v32, v127, v128, v38
	v_med3_f32 v33, v128, v129, v38
	v_med3_f32 v34, v129, v10, v38
	v_med3_f32 v35, v10, v11, v38
	v_med3_f32 v36, v11, v16, v38
	v_med3_f32 v37, v16, v17, v38
	v_max_f32_e32 v118, v22, v39
	v_med3_f32 v119, v22, v23, v39
	v_med3_f32 v120, v23, v24, v39
	v_med3_f32 v121, v24, v25, v39
	v_med3_f32 v122, v25, v26, v39
	v_med3_f32 v123, v26, v27, v39
	v_med3_f32 v124, v27, v28, v39
	v_med3_f32 v125, v28, v29, v39
	v_med3_f32 v126, v29, v30, v39
	v_med3_f32 v127, v30, v31, v39
	v_med3_f32 v128, v31, v32, v39
	v_med3_f32 v129, v32, v33, v39
	v_med3_f32 v10, v33, v34, v39
	v_med3_f32 v11, v34, v35, v39
	v_med3_f32 v16, v35, v36, v39
	v_med3_f32 v17, v36, v37, v39
	v_max_f32_e32 v22, v118, v20
	v_med3_f32 v23, v118, v119, v20
	v_med3_f32 v24, v119, v120, v20
	v_med3_f32 v25, v120, v121, v20
	v_med3_f32 v26, v121, v122, v20
	v_med3_f32 v27, v122, v123, v20
	v_med3_f32 v28, v123, v124, v20
	v_med3_f32 v29, v124, v125, v20
	v_med3_f32 v30, v125, v126, v20
	v_med3_f32 v31, v126, v127, v20
	v_med3_f32 v32, v127, v128, v20
	v_med3_f32 v33, v128, v129, v20
	v_med3_f32 v34, v129, v10, v20
	v_med3_f32 v35, v10, v11, v20
	v_med3_f32 v36, v11, v16, v20
	v_med3_f32 v37, v16, v17, v20
	v_max_f32_e32 v118, v22, v19
	v_med3_f32 v119, v22, v23, v19
	v_med3_f32 v120, v23, v24, v19
	v_med3_f32 v121, v24, v25, v19
	v_med3_f32 v122, v25, v26, v19
	v_med3_f32 v123, v26, v27, v19
	v_med3_f32 v124, v27, v28, v19
	v_med3_f32 v125, v28, v29, v19
	v_med3_f32 v126, v29, v30, v19
	v_med3_f32 v127, v30, v31, v19
	v_med3_f32 v128, v31, v32, v19
	v_med3_f32 v129, v32, v33, v19
	v_med3_f32 v10, v33, v34, v19
	v_med3_f32 v11, v34, v35, v19
	v_med3_f32 v16, v35, v36, v19
	v_med3_f32 v17, v36, v37, v19
	s_waitcnt vmcnt(1)
	v_mfma_f32_16x16x32_bf16 v[114:117], v[96:99], v[6:9], 0
	s_waitcnt vmcnt(0)
	v_mfma_f32_16x16x32_bf16 v[114:117], v[100:103], v[2:5], v[114:117]
	v_and_or_b32 v38, v110, s65, v244
	v_and_or_b32 v39, v111, s65, v245
	v_and_or_b32 v20, v112, s65, v246
	v_and_or_b32 v19, v113, s65, v247
	v_max_f32_e32 v22, v118, v38
	v_med3_f32 v23, v118, v119, v38
	v_med3_f32 v24, v119, v120, v38
	v_med3_f32 v25, v120, v121, v38
	v_med3_f32 v26, v121, v122, v38
	v_med3_f32 v27, v122, v123, v38
	v_med3_f32 v28, v123, v124, v38
	v_med3_f32 v29, v124, v125, v38
	v_med3_f32 v30, v125, v126, v38
	v_med3_f32 v31, v126, v127, v38
	v_med3_f32 v32, v127, v128, v38
	v_med3_f32 v33, v128, v129, v38
	v_med3_f32 v34, v129, v10, v38
	v_med3_f32 v35, v10, v11, v38
	v_med3_f32 v36, v11, v16, v38
	v_med3_f32 v37, v16, v17, v38
	v_max_f32_e32 v118, v22, v39
	v_med3_f32 v119, v22, v23, v39
	v_med3_f32 v120, v23, v24, v39
	v_med3_f32 v121, v24, v25, v39
	v_med3_f32 v122, v25, v26, v39
	v_med3_f32 v123, v26, v27, v39
	v_med3_f32 v124, v27, v28, v39
	v_med3_f32 v125, v28, v29, v39
	v_med3_f32 v126, v29, v30, v39
	v_med3_f32 v127, v30, v31, v39
	v_med3_f32 v128, v31, v32, v39
	v_med3_f32 v129, v32, v33, v39
	v_med3_f32 v10, v33, v34, v39
	v_med3_f32 v11, v34, v35, v39
	v_med3_f32 v16, v35, v36, v39
	v_med3_f32 v17, v36, v37, v39
	v_max_f32_e32 v22, v118, v20
	v_med3_f32 v23, v118, v119, v20
	v_med3_f32 v24, v119, v120, v20
	v_med3_f32 v25, v120, v121, v20
	v_med3_f32 v26, v121, v122, v20
	v_med3_f32 v27, v122, v123, v20
	v_med3_f32 v28, v123, v124, v20
	v_med3_f32 v29, v124, v125, v20
	v_med3_f32 v30, v125, v126, v20
	v_med3_f32 v31, v126, v127, v20
	v_med3_f32 v32, v127, v128, v20
	v_med3_f32 v33, v128, v129, v20
	v_med3_f32 v34, v129, v10, v20
	v_med3_f32 v35, v10, v11, v20
	v_med3_f32 v36, v11, v16, v20
	v_med3_f32 v37, v16, v17, v20
	v_max_f32_e32 v118, v22, v19
	v_med3_f32 v119, v22, v23, v19
	v_med3_f32 v120, v23, v24, v19
	v_med3_f32 v121, v24, v25, v19
	v_med3_f32 v122, v25, v26, v19
	v_med3_f32 v123, v26, v27, v19
	v_med3_f32 v124, v27, v28, v19
	v_med3_f32 v125, v28, v29, v19
	v_med3_f32 v126, v29, v30, v19
	v_med3_f32 v127, v30, v31, v19
	v_med3_f32 v128, v31, v32, v19
	v_med3_f32 v129, v32, v33, v19
	v_med3_f32 v10, v33, v34, v19
	v_med3_f32 v11, v34, v35, v19
	v_med3_f32 v16, v35, v36, v19
	v_med3_f32 v17, v36, v37, v19
	v_and_or_b32 v38, v114, s65, v248
	v_and_or_b32 v39, v115, s65, v249
	v_and_or_b32 v20, v116, s65, v250
	v_and_or_b32 v19, v117, s65, v251
	v_max_f32_e32 v22, v118, v38
	v_med3_f32 v23, v118, v119, v38
	v_med3_f32 v24, v119, v120, v38
	v_med3_f32 v25, v120, v121, v38
	v_med3_f32 v26, v121, v122, v38
	v_med3_f32 v27, v122, v123, v38
	v_med3_f32 v28, v123, v124, v38
	v_med3_f32 v29, v124, v125, v38
	v_med3_f32 v30, v125, v126, v38
	v_med3_f32 v31, v126, v127, v38
	v_med3_f32 v32, v127, v128, v38
	v_med3_f32 v33, v128, v129, v38
	v_med3_f32 v34, v129, v10, v38
	v_med3_f32 v35, v10, v11, v38
	v_med3_f32 v36, v11, v16, v38
	v_med3_f32 v37, v16, v17, v38
	v_max_f32_e32 v118, v22, v39
	v_med3_f32 v119, v22, v23, v39
	v_med3_f32 v120, v23, v24, v39
	v_med3_f32 v121, v24, v25, v39
	v_med3_f32 v122, v25, v26, v39
	v_med3_f32 v123, v26, v27, v39
	v_med3_f32 v124, v27, v28, v39
	v_med3_f32 v125, v28, v29, v39
	v_med3_f32 v126, v29, v30, v39
	v_med3_f32 v127, v30, v31, v39
	v_med3_f32 v128, v31, v32, v39
	v_med3_f32 v129, v32, v33, v39
	v_med3_f32 v10, v33, v34, v39
	v_med3_f32 v11, v34, v35, v39
	v_med3_f32 v16, v35, v36, v39
	v_med3_f32 v17, v36, v37, v39
	v_max_f32_e32 v22, v118, v20
	v_med3_f32 v23, v118, v119, v20
	v_med3_f32 v24, v119, v120, v20
	v_med3_f32 v25, v120, v121, v20
	v_med3_f32 v26, v121, v122, v20
	v_med3_f32 v27, v122, v123, v20
	v_med3_f32 v28, v123, v124, v20
	v_med3_f32 v29, v124, v125, v20
	v_med3_f32 v30, v125, v126, v20
	v_med3_f32 v31, v126, v127, v20
	v_med3_f32 v32, v127, v128, v20
	v_med3_f32 v33, v128, v129, v20
	v_med3_f32 v34, v129, v10, v20
	v_med3_f32 v35, v10, v11, v20
	v_med3_f32 v36, v11, v16, v20
	v_med3_f32 v37, v16, v17, v20
	v_max_f32_e32 v21, v22, v19
	v_med3_f32 v5, v22, v23, v19
	v_med3_f32 v4, v23, v24, v19
	v_med3_f32 v6, v24, v25, v19
	v_med3_f32 v7, v25, v26, v19
	v_med3_f32 v8, v26, v27, v19
	v_med3_f32 v9, v27, v28, v19
	v_med3_f32 v10, v28, v29, v19
	v_med3_f32 v11, v29, v30, v19
	v_med3_f32 v12, v30, v31, v19
	v_med3_f32 v13, v31, v32, v19
	v_med3_f32 v14, v32, v33, v19
	v_med3_f32 v15, v33, v34, v19
	v_med3_f32 v16, v34, v35, v19
	v_med3_f32 v17, v35, v36, v19
	v_med3_f32 v0, v36, v37, v19
	ds_bpermute_b32 v2, v214, v21
	ds_bpermute_b32 v34, v214, v0
	ds_bpermute_b32 v33, v214, v17
	ds_bpermute_b32 v32, v214, v16
	ds_bpermute_b32 v31, v214, v15
	ds_bpermute_b32 v30, v214, v14
	s_waitcnt lgkmcnt(5)
	v_max_f32_e32 v2, v2, v2
	ds_bpermute_b32 v29, v214, v13
	v_max_f32_e32 v0, v0, v2
	s_waitcnt lgkmcnt(5)
	v_max_f32_e32 v2, v34, v34
	ds_bpermute_b32 v28, v214, v12
	v_max_f32_e32 v2, v21, v2
	s_waitcnt lgkmcnt(5)
	v_max_f32_e32 v21, v33, v33
	ds_bpermute_b32 v3, v214, v5
	ds_bpermute_b32 v27, v214, v11
	v_max_f32_e32 v5, v5, v21
	s_waitcnt lgkmcnt(6)
	v_max_f32_e32 v21, v32, v32
	ds_bpermute_b32 v20, v214, v4
	ds_bpermute_b32 v26, v214, v10
	v_max_f32_e32 v4, v4, v21
	s_waitcnt lgkmcnt(7)
	v_max_f32_e32 v21, v31, v31
	ds_bpermute_b32 v22, v214, v6
	ds_bpermute_b32 v25, v214, v9
	v_max_f32_e32 v6, v6, v21
	s_waitcnt lgkmcnt(8)
	v_max_f32_e32 v21, v30, v30
	ds_bpermute_b32 v23, v214, v7
	ds_bpermute_b32 v24, v214, v8
	v_max_f32_e32 v7, v7, v21
	s_waitcnt lgkmcnt(9)
	v_max_f32_e32 v21, v29, v29
	v_max_f32_e32 v8, v8, v21
	s_waitcnt lgkmcnt(8)
	v_max_f32_e32 v21, v28, v28
	v_max_f32_e32 v9, v9, v21
	s_waitcnt lgkmcnt(6)
	v_max_f32_e32 v21, v27, v27
	v_max_f32_e32 v10, v10, v21
	s_waitcnt lgkmcnt(4)
	v_max_f32_e32 v21, v26, v26
	v_max_f32_e32 v11, v11, v21
	s_waitcnt lgkmcnt(2)
	v_max_f32_e32 v21, v25, v25
	v_max_f32_e32 v12, v12, v21
	s_waitcnt lgkmcnt(0)
	v_max_f32_e32 v21, v24, v24
	v_max_f32_e32 v13, v13, v21
	v_max_f32_e32 v21, v23, v23
	v_max_f32_e32 v14, v14, v21
	v_max_f32_e32 v21, v22, v22
	v_max_f32_e32 v20, v20, v20
	v_max_f32_e32 v3, v3, v3
	v_max_f32_e32 v15, v15, v21
	v_max_f32_e32 v16, v16, v20
	v_max_f32_e32 v3, v17, v3
	v_max_f32_e32 v17, v2, v11
	v_min_f32_e32 v2, v2, v11
	v_max_f32_e32 v11, v5, v12
	v_min_f32_e32 v5, v5, v12
	v_max_f32_e32 v12, v4, v13
	v_min_f32_e32 v4, v4, v13
	v_max_f32_e32 v13, v6, v14
	v_min_f32_e32 v6, v6, v14
	v_max_f32_e32 v14, v7, v15
	v_min_f32_e32 v7, v7, v15
	v_max_f32_e32 v15, v8, v16
	v_min_f32_e32 v8, v8, v16
	v_max_f32_e32 v16, v9, v3
	v_min_f32_e32 v3, v9, v3
	v_max_f32_e32 v9, v10, v0
	v_min_f32_e32 v0, v10, v0
	v_max_f32_e32 v10, v17, v14
	v_min_f32_e32 v14, v17, v14
	v_max_f32_e32 v17, v11, v15
	v_min_f32_e32 v11, v11, v15
	v_max_f32_e32 v15, v12, v16
	v_min_f32_e32 v12, v12, v16
	v_max_f32_e32 v16, v13, v9
	v_min_f32_e32 v9, v13, v9
	v_max_f32_e32 v13, v2, v7
	v_min_f32_e32 v2, v2, v7
	v_max_f32_e32 v7, v5, v8
	v_min_f32_e32 v5, v5, v8
	v_max_f32_e32 v8, v4, v3
	v_min_f32_e32 v3, v4, v3
	v_max_f32_e32 v4, v6, v0
	v_min_f32_e32 v0, v6, v0
	v_max_f32_e32 v6, v10, v15
	v_min_f32_e32 v10, v10, v15
	v_max_f32_e32 v15, v17, v16
	v_min_f32_e32 v16, v17, v16
	v_max_f32_e32 v17, v14, v12
	v_min_f32_e32 v12, v14, v12
	v_max_f32_e32 v14, v11, v9
	v_min_f32_e32 v9, v11, v9
	v_max_f32_e32 v11, v13, v8
	v_min_f32_e32 v8, v13, v8
	v_max_f32_e32 v13, v7, v4
	v_min_f32_e32 v4, v7, v4
	v_max_f32_e32 v20, v2, v3
	v_min_f32_e32 v3, v2, v3
	v_max_f32_e32 v22, v5, v0
	v_min_f32_e32 v25, v5, v0
	v_max_f32_e32 v24, v6, v15
	v_min_f32_e32 v7, v6, v15
	v_max_f32_e32 v15, v10, v16
	v_min_f32_e32 v2, v10, v16
	v_max_f32_e32 v23, v17, v14
	v_min_f32_e32 v6, v17, v14
	v_max_f32_e32 v14, v12, v9
	v_min_f32_e32 v0, v12, v9
	v_max_f32_e32 v29, v11, v13
	v_min_f32_e32 v11, v11, v13
	v_max_f32_e32 v21, v8, v4
	v_min_f32_e32 v5, v8, v4
	v_max_f32_e32 v26, v20, v22
	v_min_f32_e32 v8, v20, v22
	v_max_f32_e32 v16, v3, v25
	v_min_f32_e32 v3, v3, v25
	ds_bpermute_b32 v4, v215, v24
	ds_bpermute_b32 v22, v215, v7
	ds_bpermute_b32 v12, v215, v15
	ds_bpermute_b32 v30, v215, v2
	ds_bpermute_b32 v9, v215, v23
	ds_bpermute_b32 v27, v215, v6
	ds_bpermute_b32 v17, v215, v14
	ds_bpermute_b32 v32, v215, v0
	ds_bpermute_b32 v10, v215, v29
	ds_bpermute_b32 v28, v215, v11
	ds_bpermute_b32 v20, v215, v21
	ds_bpermute_b32 v33, v215, v5
	ds_bpermute_b32 v13, v215, v26
	ds_bpermute_b32 v31, v215, v8
	ds_bpermute_b32 v25, v215, v16
	ds_bpermute_b32 v34, v215, v3
	s_and_saveexec_b64 s[0:1], s[28:29]
	s_cbranch_execz .LBB0_858
	s_waitcnt lgkmcnt(3)
	v_max_f32_e32 v13, v13, v13
	v_max_f32_e32 v2, v2, v2
	s_waitcnt lgkmcnt(1)
	v_max_f32_e32 v25, v25, v25
	v_max_f32_e32 v7, v7, v7
	v_max_f32_e32 v13, v2, v13
	v_max_f32_e32 v2, v9, v9
	v_max_f32_e32 v5, v5, v5
	s_waitcnt lgkmcnt(0)
	v_max_f32_e32 v19, v34, v34
	v_max_f32_e32 v24, v24, v24
	v_max_f32_e32 v25, v7, v25
	v_max_f32_e32 v7, v17, v17
	v_max_f32_e32 v17, v20, v20
	v_max_f32_e32 v6, v6, v6
	v_max_f32_e32 v20, v5, v2
	v_max_f32_e32 v2, v10, v10
	v_max_f32_e32 v0, v0, v0
	v_max_f32_e32 v19, v24, v19
	v_max_f32_e32 v24, v32, v32
	v_max_f32_e32 v29, v29, v29
	v_max_f32_e32 v32, v33, v33
	v_max_f32_e32 v23, v23, v23
	v_max_f32_e32 v30, v30, v30
	v_max_f32_e32 v26, v26, v26
	v_max_f32_e32 v31, v31, v31
	v_max_f32_e32 v15, v15, v15
	v_max_f32_e32 v27, v27, v27
	v_max_f32_e32 v21, v21, v21
	v_max_f32_e32 v28, v28, v28
	v_max_f32_e32 v14, v14, v14
	v_max_f32_e32 v22, v22, v22
	v_max_f32_e32 v16, v16, v16
	v_max_f32_e32 v11, v11, v11
	v_max_f32_e32 v17, v6, v17
	v_max_f32_e32 v6, v12, v12
	v_max_f32_e32 v8, v8, v8
	v_max_f32_e32 v0, v0, v2
	v_max_f32_e32 v2, v4, v4
	v_max_f32_e32 v3, v3, v3
	v_max_f32_e32 v24, v29, v24
	v_max_f32_e32 v23, v23, v32
	v_max_f32_e32 v26, v26, v30
	v_max_f32_e32 v15, v15, v31
	v_max_f32_e32 v21, v21, v27
	v_max_f32_e32 v14, v14, v28
	v_max_f32_e32 v16, v16, v22
	v_max_f32_e32 v11, v11, v7
	v_max_f32_e32 v12, v8, v6
	v_max_f32_e32 v10, v3, v2
	v_min_f32_e32 v29, v19, v24
	v_min_f32_e32 v30, v23, v26
	v_min_f32_e32 v27, v15, v21
	v_min_f32_e32 v22, v14, v16
	v_min_f32_e32 v7, v25, v11
	v_min_f32_e32 v6, v17, v12
	v_min_f32_e32 v9, v13, v20
	v_min_f32_e32 v33, v0, v10
	v_min_f32_e32 v32, v29, v30
	v_min_f32_e32 v28, v27, v22
	v_min_f32_e32 v8, v7, v6
	v_min_f32_e32 v2, v9, v33
	v_min_f32_e32 v31, v32, v28
	v_min_f32_e32 v3, v8, v2
	v_max_f32_e32 v28, v32, v28
	v_max_f32_e32 v2, v8, v2
	v_min_f32_e32 v5, v31, v3
	v_max_f32_e32 v4, v31, v3
	v_min_f32_e32 v3, v28, v2
	v_max_f32_e32 v2, v28, v2
	v_max_f32_e32 v28, v29, v30
	v_max_f32_e32 v22, v27, v22
	v_max_f32_e32 v6, v7, v6
	v_max_f32_e32 v7, v9, v33
	v_min_f32_e32 v8, v28, v22
	v_min_f32_e32 v27, v6, v7
	v_max_f32_e32 v22, v28, v22
	v_max_f32_e32 v6, v6, v7
	v_min_f32_e32 v7, v22, v6
	v_max_f32_e32 v6, v22, v6
	v_max_f32_e32 v19, v19, v24
	v_max_f32_e32 v22, v23, v26
	v_max_f32_e32 v15, v15, v21
	v_max_f32_e32 v14, v14, v16
	v_max_f32_e32 v24, v25, v11
	v_max_f32_e32 v17, v17, v12
	v_max_f32_e32 v20, v13, v20
	v_max_f32_e32 v0, v0, v10
	v_min_f32_e32 v23, v19, v22
	v_min_f32_e32 v16, v15, v14
	v_min_f32_e32 v11, v24, v17
	v_min_f32_e32 v10, v20, v0
	v_min_f32_e32 v21, v23, v16
	v_min_f32_e32 v12, v11, v10
	v_min_f32_e32 v13, v21, v12
	v_max_f32_e32 v12, v21, v12
	v_max_f32_e32 v16, v23, v16
	v_max_f32_e32 v10, v11, v10
	v_max_f32_e32 v19, v19, v22
	v_max_f32_e32 v14, v15, v14
	v_max_f32_e32 v21, v24, v17
	v_max_f32_e32 v0, v20, v0
	v_min_f32_e32 v11, v16, v10
	v_max_f32_e32 v10, v16, v10
	v_min_f32_e32 v15, v19, v14
	v_min_f32_e32 v16, v21, v0
	v_max_f32_e32 v14, v19, v14
	v_max_f32_e32 v0, v21, v0
	v_min_f32_e32 v17, v15, v16
	v_max_f32_e32 v16, v15, v16
	v_min_f32_e32 v15, v14, v0
	v_max_f32_e32 v14, v14, v0
	v_lshlrev_b32_e32 v0, 10, v18
	v_add3_u32 v0, v252, v0, s20
	v_min_f32_e32 v9, v8, v27
	v_max_f32_e32 v8, v8, v27
	ds_write_b128 v0, v[14:17]
	ds_write_b128 v0, v[10:13] offset:16
	ds_write_b128 v0, v[6:9] offset:32
	ds_write_b128 v0, v[2:5] offset:48
	s_branch .LBB0_858

.LBB0_870:
	v_add_u32_e32 v0, s1, v199
	ds_read_b128 v[2:5], v0
	ds_read_b128 v[6:9], v0 offset:16
	ds_read_b128 v[14:17], v0 offset:32
	ds_read_b128 v[26:29], v0 offset:48
	s_waitcnt lgkmcnt(3)
	v_readfirstlane_b32 s20, v2
	s_lshl_b64 s[42:43], s[20:21], 11
	v_lshl_add_u64 v[22:23], v[140:141], 0, s[42:43]
	global_load_dwordx4 v[126:129], v[22:23], off
	v_readfirstlane_b32 s20, v3
	s_lshl_b64 s[42:43], s[20:21], 11
	v_lshl_add_u64 v[24:25], v[140:141], 0, s[42:43]
	global_load_dwordx4 v[122:125], v[24:25], off
	v_readfirstlane_b32 s20, v4
	s_lshl_b64 s[42:43], s[20:21], 11
	v_lshl_add_u64 v[20:21], v[140:141], 0, s[42:43]
	global_load_dwordx4 v[118:121], v[20:21], off
	v_readfirstlane_b32 s20, v5
	s_lshl_b64 s[42:43], s[20:21], 11
	s_waitcnt lgkmcnt(2)
	v_readfirstlane_b32 s20, v6
	v_lshl_add_u64 v[18:19], v[140:141], 0, s[42:43]
	s_lshl_b64 s[42:43], s[20:21], 11
	v_readfirstlane_b32 s20, v7
	v_lshl_add_u64 v[10:11], v[140:141], 0, s[42:43]
	s_lshl_b64 s[42:43], s[20:21], 11
	v_readfirstlane_b32 s20, v8
	v_lshl_add_u64 v[2:3], v[140:141], 0, s[42:43]
	s_lshl_b64 s[42:43], s[20:21], 11
	v_readfirstlane_b32 s20, v9
	v_lshl_add_u64 v[4:5], v[140:141], 0, s[42:43]
	s_lshl_b64 s[42:43], s[20:21], 11
	s_waitcnt lgkmcnt(1)
	v_readfirstlane_b32 s20, v14
	v_lshl_add_u64 v[6:7], v[140:141], 0, s[42:43]
	s_lshl_b64 s[42:43], s[20:21], 11
	v_readfirstlane_b32 s20, v15
	global_load_dwordx4 v[114:117], v[18:19], off
	v_lshl_add_u64 v[8:9], v[140:141], 0, s[42:43]
	s_lshl_b64 s[42:43], s[20:21], 11
	v_readfirstlane_b32 s20, v16
	v_lshl_add_u64 v[12:13], v[140:141], 0, s[42:43]
	s_lshl_b64 s[42:43], s[20:21], 11
	v_readfirstlane_b32 s20, v17
	v_lshl_add_u64 v[14:15], v[140:141], 0, s[42:43]
	s_lshl_b64 s[42:43], s[20:21], 11
	s_waitcnt lgkmcnt(0)
	v_readfirstlane_b32 s20, v26
	v_lshl_add_u64 v[16:17], v[140:141], 0, s[42:43]
	s_lshl_b64 s[42:43], s[20:21], 11
	v_readfirstlane_b32 s20, v27
	v_lshl_add_u64 v[188:189], v[140:141], 0, s[42:43]
	s_lshl_b64 s[42:43], s[20:21], 11
	v_readfirstlane_b32 s20, v28
	v_lshl_add_u64 v[190:191], v[140:141], 0, s[42:43]
	s_lshl_b64 s[42:43], s[20:21], 11
	v_readfirstlane_b32 s20, v29
	v_lshl_add_u64 v[192:193], v[140:141], 0, s[42:43]
	s_lshl_b64 s[42:43], s[20:21], 11
	v_lshl_add_u64 v[194:195], v[140:141], 0, s[42:43]
	global_load_dwordx4 v[110:113], v[10:11], off
	global_load_dwordx4 v[90:93], v[12:13], off
	global_load_dwordx4 v[106:109], v[2:3], off
	global_load_dwordx4 v[102:105], v[4:5], off
	global_load_dwordx4 v[98:101], v[6:7], off
	global_load_dwordx4 v[94:97], v[8:9], off
	global_load_dwordx4 v[86:89], v[14:15], off
	global_load_dwordx4 v[82:85], v[16:17], off
	global_load_dwordx4 v[78:81], v[188:189], off
	global_load_dwordx4 v[74:77], v[190:191], off
	global_load_dwordx4 v[70:73], v[192:193], off
	global_load_dwordx4 v[66:69], v[194:195], off
	global_load_dwordx4 v[62:65], v[22:23], off offset:1024
	global_load_dwordx4 v[58:61], v[24:25], off offset:1024
	global_load_dwordx4 v[54:57], v[20:21], off offset:1024
	global_load_dwordx4 v[50:53], v[18:19], off offset:1024
	global_load_dwordx4 v[46:49], v[10:11], off offset:1024
	global_load_dwordx4 v[42:45], v[2:3], off offset:1024
	global_load_dwordx4 v[38:41], v[4:5], off offset:1024
	global_load_dwordx4 v[34:37], v[6:7], off offset:1024
	global_load_dwordx4 v[30:33], v[8:9], off offset:1024
	global_load_dwordx4 v[26:29], v[12:13], off offset:1024
	global_load_dwordx4 v[22:25], v[14:15], off offset:1024
	global_load_dwordx4 v[18:21], v[16:17], off offset:1024
	s_nop 0
	global_load_dwordx4 v[14:17], v[188:189], off offset:1024
	global_load_dwordx4 v[10:13], v[190:191], off offset:1024
	global_load_dwordx4 v[6:9], v[192:193], off offset:1024
	global_load_dwordx4 v[2:5], v[194:195], off offset:1024
	s_waitcnt vmcnt(31)
	v_cvt_pk_f32_fp8_e32 v[188:189], v126
	v_cvt_pk_f32_fp8_sdwa v[190:191], v126 src0_sel:WORD_1
	v_pk_fma_f32 v[188:189], v[188:189], v[154:155], 0 op_sel_hi:[1,1,0]
	s_nop 0
	v_pk_fma_f32 v[188:189], v[190:191], v[156:157], v[188:189]
	v_cvt_pk_f32_fp8_e32 v[190:191], v127
	v_cvt_pk_f32_fp8_sdwa v[126:127], v127 src0_sel:WORD_1
	v_pk_fma_f32 v[188:189], v[190:191], v[158:159], v[188:189]
	s_nop 0
	v_pk_fma_f32 v[126:127], v[126:127], v[162:163], v[188:189]
	v_cvt_pk_f32_fp8_e32 v[188:189], v128
	v_pk_fma_f32 v[126:127], v[188:189], v[164:165], v[126:127]
	v_cvt_pk_f32_fp8_sdwa v[188:189], v128 src0_sel:WORD_1
	v_pk_fma_f32 v[126:127], v[188:189], v[166:167], v[126:127]
	v_cvt_pk_f32_fp8_e32 v[188:189], v129
	v_cvt_pk_f32_fp8_sdwa v[128:129], v129 src0_sel:WORD_1
	v_pk_fma_f32 v[126:127], v[188:189], v[168:169], v[126:127]
	s_nop 0
	v_pk_fma_f32 v[126:127], v[128:129], v[170:171], v[126:127]
	s_waitcnt vmcnt(30)
	v_cvt_pk_f32_fp8_sdwa v[128:129], v122 src0_sel:WORD_1
	v_add_f32_e32 v0, v126, v127
	v_cvt_pk_f32_fp8_e32 v[126:127], v122
	v_pk_fma_f32 v[126:127], v[126:127], v[154:155], 0 op_sel_hi:[1,1,0]
	s_nop 0
	v_pk_fma_f32 v[126:127], v[128:129], v[156:157], v[126:127]
	v_cvt_pk_f32_fp8_e32 v[128:129], v123
	v_cvt_pk_f32_fp8_sdwa v[122:123], v123 src0_sel:WORD_1
	v_pk_fma_f32 v[126:127], v[128:129], v[158:159], v[126:127]
	s_nop 0
	v_pk_fma_f32 v[122:123], v[122:123], v[162:163], v[126:127]
	v_cvt_pk_f32_fp8_e32 v[126:127], v124
	v_pk_fma_f32 v[122:123], v[126:127], v[164:165], v[122:123]
	v_cvt_pk_f32_fp8_sdwa v[126:127], v124 src0_sel:WORD_1
	v_pk_fma_f32 v[122:123], v[126:127], v[166:167], v[122:123]
	v_cvt_pk_f32_fp8_e32 v[126:127], v125
	v_cvt_pk_f32_fp8_sdwa v[124:125], v125 src0_sel:WORD_1
	v_pk_fma_f32 v[122:123], v[126:127], v[168:169], v[122:123]
	s_nop 0
	v_pk_fma_f32 v[122:123], v[124:125], v[170:171], v[122:123]
	s_waitcnt vmcnt(29)
	v_cvt_pk_f32_fp8_sdwa v[124:125], v118 src0_sel:WORD_1
	v_add_f32_e32 v126, v122, v123
	v_cvt_pk_f32_fp8_e32 v[122:123], v118
	v_pk_fma_f32 v[122:123], v[122:123], v[154:155], 0 op_sel_hi:[1,1,0]
	s_nop 0
	v_pk_fma_f32 v[122:123], v[124:125], v[156:157], v[122:123]
	v_cvt_pk_f32_fp8_e32 v[124:125], v119
	v_cvt_pk_f32_fp8_sdwa v[118:119], v119 src0_sel:WORD_1
	v_pk_fma_f32 v[122:123], v[124:125], v[158:159], v[122:123]
	s_nop 0
	v_pk_fma_f32 v[118:119], v[118:119], v[162:163], v[122:123]
	v_cvt_pk_f32_fp8_e32 v[122:123], v120
	v_pk_fma_f32 v[118:119], v[122:123], v[164:165], v[118:119]
	v_cvt_pk_f32_fp8_sdwa v[122:123], v120 src0_sel:WORD_1
	v_pk_fma_f32 v[118:119], v[122:123], v[166:167], v[118:119]
	v_cvt_pk_f32_fp8_e32 v[122:123], v121
	v_cvt_pk_f32_fp8_sdwa v[120:121], v121 src0_sel:WORD_1
	v_pk_fma_f32 v[118:119], v[122:123], v[168:169], v[118:119]
	s_nop 0
	v_pk_fma_f32 v[118:119], v[120:121], v[170:171], v[118:119]
	s_waitcnt vmcnt(28)
	v_cvt_pk_f32_fp8_sdwa v[120:121], v114 src0_sel:WORD_1
	v_add_f32_e32 v122, v118, v119
	v_cvt_pk_f32_fp8_e32 v[118:119], v114
	v_pk_fma_f32 v[118:119], v[118:119], v[154:155], 0 op_sel_hi:[1,1,0]
	s_nop 0
	v_pk_fma_f32 v[118:119], v[120:121], v[156:157], v[118:119]
	v_cvt_pk_f32_fp8_e32 v[120:121], v115
	v_cvt_pk_f32_fp8_sdwa v[114:115], v115 src0_sel:WORD_1
	v_pk_fma_f32 v[118:119], v[120:121], v[158:159], v[118:119]
	s_nop 0
	v_pk_fma_f32 v[114:115], v[114:115], v[162:163], v[118:119]
	v_cvt_pk_f32_fp8_e32 v[118:119], v116
	v_pk_fma_f32 v[114:115], v[118:119], v[164:165], v[114:115]
	v_cvt_pk_f32_fp8_sdwa v[118:119], v116 src0_sel:WORD_1
	v_pk_fma_f32 v[114:115], v[118:119], v[166:167], v[114:115]
	v_cvt_pk_f32_fp8_e32 v[118:119], v117
	v_cvt_pk_f32_fp8_sdwa v[116:117], v117 src0_sel:WORD_1
	v_pk_fma_f32 v[114:115], v[118:119], v[168:169], v[114:115]
	s_nop 0
	v_pk_fma_f32 v[114:115], v[116:117], v[170:171], v[114:115]
	s_waitcnt vmcnt(27)
	v_cvt_pk_f32_fp8_sdwa v[116:117], v110 src0_sel:WORD_1
	v_add_f32_e32 v118, v114, v115
	v_cvt_pk_f32_fp8_e32 v[114:115], v110
	v_pk_fma_f32 v[114:115], v[114:115], v[154:155], 0 op_sel_hi:[1,1,0]
	s_nop 0
	v_pk_fma_f32 v[114:115], v[116:117], v[156:157], v[114:115]
	v_cvt_pk_f32_fp8_e32 v[116:117], v111
	v_cvt_pk_f32_fp8_sdwa v[110:111], v111 src0_sel:WORD_1
	v_pk_fma_f32 v[114:115], v[116:117], v[158:159], v[114:115]
	s_nop 0
	v_pk_fma_f32 v[110:111], v[110:111], v[162:163], v[114:115]
	v_cvt_pk_f32_fp8_e32 v[114:115], v112
	v_pk_fma_f32 v[110:111], v[114:115], v[164:165], v[110:111]
	v_cvt_pk_f32_fp8_sdwa v[114:115], v112 src0_sel:WORD_1
	v_pk_fma_f32 v[110:111], v[114:115], v[166:167], v[110:111]
	v_cvt_pk_f32_fp8_e32 v[114:115], v113
	v_cvt_pk_f32_fp8_sdwa v[112:113], v113 src0_sel:WORD_1
	v_pk_fma_f32 v[110:111], v[114:115], v[168:169], v[110:111]
	s_nop 0
	v_pk_fma_f32 v[110:111], v[112:113], v[170:171], v[110:111]
	s_waitcnt vmcnt(25)
	v_cvt_pk_f32_fp8_sdwa v[112:113], v106 src0_sel:WORD_1
	v_add_f32_e32 v114, v110, v111
	v_cvt_pk_f32_fp8_e32 v[110:111], v106
	v_pk_fma_f32 v[110:111], v[110:111], v[154:155], 0 op_sel_hi:[1,1,0]
	s_nop 0
	v_pk_fma_f32 v[110:111], v[112:113], v[156:157], v[110:111]
	v_cvt_pk_f32_fp8_e32 v[112:113], v107
	v_cvt_pk_f32_fp8_sdwa v[106:107], v107 src0_sel:WORD_1
	v_pk_fma_f32 v[110:111], v[112:113], v[158:159], v[110:111]
	s_nop 0
	v_pk_fma_f32 v[106:107], v[106:107], v[162:163], v[110:111]
	v_cvt_pk_f32_fp8_e32 v[110:111], v108
	v_pk_fma_f32 v[106:107], v[110:111], v[164:165], v[106:107]
	v_cvt_pk_f32_fp8_sdwa v[110:111], v108 src0_sel:WORD_1
	v_pk_fma_f32 v[106:107], v[110:111], v[166:167], v[106:107]
	v_cvt_pk_f32_fp8_e32 v[110:111], v109
	v_cvt_pk_f32_fp8_sdwa v[108:109], v109 src0_sel:WORD_1
	v_pk_fma_f32 v[106:107], v[110:111], v[168:169], v[106:107]
	s_nop 0
	v_pk_fma_f32 v[106:107], v[108:109], v[170:171], v[106:107]
	s_waitcnt vmcnt(24)
	v_cvt_pk_f32_fp8_sdwa v[108:109], v102 src0_sel:WORD_1
	v_add_f32_e32 v110, v106, v107
	v_cvt_pk_f32_fp8_e32 v[106:107], v102
	v_pk_fma_f32 v[106:107], v[106:107], v[154:155], 0 op_sel_hi:[1,1,0]
	s_nop 0
	v_pk_fma_f32 v[106:107], v[108:109], v[156:157], v[106:107]
	v_cvt_pk_f32_fp8_e32 v[108:109], v103
	v_cvt_pk_f32_fp8_sdwa v[102:103], v103 src0_sel:WORD_1
	v_pk_fma_f32 v[106:107], v[108:109], v[158:159], v[106:107]
	s_nop 0
	v_pk_fma_f32 v[102:103], v[102:103], v[162:163], v[106:107]
	v_cvt_pk_f32_fp8_e32 v[106:107], v104
	v_pk_fma_f32 v[102:103], v[106:107], v[164:165], v[102:103]
	v_cvt_pk_f32_fp8_sdwa v[106:107], v104 src0_sel:WORD_1
	v_pk_fma_f32 v[102:103], v[106:107], v[166:167], v[102:103]
	v_cvt_pk_f32_fp8_e32 v[106:107], v105
	v_cvt_pk_f32_fp8_sdwa v[104:105], v105 src0_sel:WORD_1
	v_pk_fma_f32 v[102:103], v[106:107], v[168:169], v[102:103]
	s_nop 0
	v_pk_fma_f32 v[102:103], v[104:105], v[170:171], v[102:103]
	s_waitcnt vmcnt(23)
	v_cvt_pk_f32_fp8_sdwa v[104:105], v98 src0_sel:WORD_1
	v_add_f32_e32 v106, v102, v103
	v_cvt_pk_f32_fp8_e32 v[102:103], v98
	v_pk_fma_f32 v[102:103], v[102:103], v[154:155], 0 op_sel_hi:[1,1,0]
	s_nop 0
	v_pk_fma_f32 v[102:103], v[104:105], v[156:157], v[102:103]
	v_cvt_pk_f32_fp8_e32 v[104:105], v99
	v_cvt_pk_f32_fp8_sdwa v[98:99], v99 src0_sel:WORD_1
	v_pk_fma_f32 v[102:103], v[104:105], v[158:159], v[102:103]
	s_nop 0
	v_pk_fma_f32 v[98:99], v[98:99], v[162:163], v[102:103]
	v_cvt_pk_f32_fp8_e32 v[102:103], v100
	v_pk_fma_f32 v[98:99], v[102:103], v[164:165], v[98:99]
	v_cvt_pk_f32_fp8_sdwa v[102:103], v100 src0_sel:WORD_1
	v_pk_fma_f32 v[98:99], v[102:103], v[166:167], v[98:99]
	v_cvt_pk_f32_fp8_e32 v[102:103], v101
	v_cvt_pk_f32_fp8_sdwa v[100:101], v101 src0_sel:WORD_1
	v_pk_fma_f32 v[98:99], v[102:103], v[168:169], v[98:99]
	s_nop 0
	v_pk_fma_f32 v[98:99], v[100:101], v[170:171], v[98:99]
	s_waitcnt vmcnt(22)
	v_cvt_pk_f32_fp8_sdwa v[100:101], v94 src0_sel:WORD_1
	v_add_f32_e32 v102, v98, v99
	v_cvt_pk_f32_fp8_e32 v[98:99], v94
	v_pk_fma_f32 v[98:99], v[98:99], v[154:155], 0 op_sel_hi:[1,1,0]
	s_nop 0
	v_pk_fma_f32 v[98:99], v[100:101], v[156:157], v[98:99]
	v_cvt_pk_f32_fp8_e32 v[100:101], v95
	v_cvt_pk_f32_fp8_sdwa v[94:95], v95 src0_sel:WORD_1
	v_pk_fma_f32 v[98:99], v[100:101], v[158:159], v[98:99]
	s_nop 0
	v_pk_fma_f32 v[94:95], v[94:95], v[162:163], v[98:99]
	v_cvt_pk_f32_fp8_e32 v[98:99], v96
	v_pk_fma_f32 v[94:95], v[98:99], v[164:165], v[94:95]
	v_cvt_pk_f32_fp8_sdwa v[98:99], v96 src0_sel:WORD_1
	v_pk_fma_f32 v[94:95], v[98:99], v[166:167], v[94:95]
	v_cvt_pk_f32_fp8_e32 v[98:99], v97
	v_cvt_pk_f32_fp8_sdwa v[96:97], v97 src0_sel:WORD_1
	v_pk_fma_f32 v[94:95], v[98:99], v[168:169], v[94:95]
	s_nop 0
	v_pk_fma_f32 v[94:95], v[96:97], v[170:171], v[94:95]
	v_cvt_pk_f32_fp8_sdwa v[96:97], v90 src0_sel:WORD_1
	v_add_f32_e32 v98, v94, v95
	v_cvt_pk_f32_fp8_e32 v[94:95], v90
	v_pk_fma_f32 v[94:95], v[94:95], v[154:155], 0 op_sel_hi:[1,1,0]
	s_nop 0
	v_pk_fma_f32 v[94:95], v[96:97], v[156:157], v[94:95]
	v_cvt_pk_f32_fp8_e32 v[96:97], v91
	v_cvt_pk_f32_fp8_sdwa v[90:91], v91 src0_sel:WORD_1
	v_pk_fma_f32 v[94:95], v[96:97], v[158:159], v[94:95]
	s_nop 0
	v_pk_fma_f32 v[90:91], v[90:91], v[162:163], v[94:95]
	v_cvt_pk_f32_fp8_e32 v[94:95], v92
	v_pk_fma_f32 v[90:91], v[94:95], v[164:165], v[90:91]
	v_cvt_pk_f32_fp8_sdwa v[94:95], v92 src0_sel:WORD_1
	v_pk_fma_f32 v[90:91], v[94:95], v[166:167], v[90:91]
	v_cvt_pk_f32_fp8_e32 v[94:95], v93
	v_cvt_pk_f32_fp8_sdwa v[92:93], v93 src0_sel:WORD_1
	v_pk_fma_f32 v[90:91], v[94:95], v[168:169], v[90:91]
	s_nop 0
	v_pk_fma_f32 v[90:91], v[92:93], v[170:171], v[90:91]
	s_waitcnt vmcnt(21)
	v_cvt_pk_f32_fp8_sdwa v[92:93], v86 src0_sel:WORD_1
	v_add_f32_e32 v94, v90, v91
	v_cvt_pk_f32_fp8_e32 v[90:91], v86
	v_pk_fma_f32 v[90:91], v[90:91], v[154:155], 0 op_sel_hi:[1,1,0]
	s_nop 0
	v_pk_fma_f32 v[90:91], v[92:93], v[156:157], v[90:91]
	v_cvt_pk_f32_fp8_e32 v[92:93], v87
	v_cvt_pk_f32_fp8_sdwa v[86:87], v87 src0_sel:WORD_1
	v_pk_fma_f32 v[90:91], v[92:93], v[158:159], v[90:91]
	s_nop 0
	v_pk_fma_f32 v[86:87], v[86:87], v[162:163], v[90:91]
	v_cvt_pk_f32_fp8_e32 v[90:91], v88
	v_pk_fma_f32 v[86:87], v[90:91], v[164:165], v[86:87]
	v_cvt_pk_f32_fp8_sdwa v[90:91], v88 src0_sel:WORD_1
	v_pk_fma_f32 v[86:87], v[90:91], v[166:167], v[86:87]
	v_cvt_pk_f32_fp8_e32 v[90:91], v89
	v_cvt_pk_f32_fp8_sdwa v[88:89], v89 src0_sel:WORD_1
	v_pk_fma_f32 v[86:87], v[90:91], v[168:169], v[86:87]
	s_nop 0
	v_pk_fma_f32 v[86:87], v[88:89], v[170:171], v[86:87]
	s_waitcnt vmcnt(20)
	v_cvt_pk_f32_fp8_sdwa v[88:89], v82 src0_sel:WORD_1
	v_add_f32_e32 v90, v86, v87
	v_cvt_pk_f32_fp8_e32 v[86:87], v82
	v_pk_fma_f32 v[86:87], v[86:87], v[154:155], 0 op_sel_hi:[1,1,0]
	s_nop 0
	v_pk_fma_f32 v[86:87], v[88:89], v[156:157], v[86:87]
	v_cvt_pk_f32_fp8_e32 v[88:89], v83
	v_cvt_pk_f32_fp8_sdwa v[82:83], v83 src0_sel:WORD_1
	v_pk_fma_f32 v[86:87], v[88:89], v[158:159], v[86:87]
	s_nop 0
	v_pk_fma_f32 v[82:83], v[82:83], v[162:163], v[86:87]
	v_cvt_pk_f32_fp8_e32 v[86:87], v84
	v_pk_fma_f32 v[82:83], v[86:87], v[164:165], v[82:83]
	v_cvt_pk_f32_fp8_sdwa v[86:87], v84 src0_sel:WORD_1
	v_pk_fma_f32 v[82:83], v[86:87], v[166:167], v[82:83]
	v_cvt_pk_f32_fp8_e32 v[86:87], v85
	v_cvt_pk_f32_fp8_sdwa v[84:85], v85 src0_sel:WORD_1
	v_pk_fma_f32 v[82:83], v[86:87], v[168:169], v[82:83]
	s_nop 0
	v_pk_fma_f32 v[82:83], v[84:85], v[170:171], v[82:83]
	s_waitcnt vmcnt(19)
	v_cvt_pk_f32_fp8_sdwa v[84:85], v78 src0_sel:WORD_1
	v_add_f32_e32 v86, v82, v83
	v_cvt_pk_f32_fp8_e32 v[82:83], v78
	v_pk_fma_f32 v[82:83], v[82:83], v[154:155], 0 op_sel_hi:[1,1,0]
	s_nop 0
	v_pk_fma_f32 v[82:83], v[84:85], v[156:157], v[82:83]
	v_cvt_pk_f32_fp8_e32 v[84:85], v79
	v_cvt_pk_f32_fp8_sdwa v[78:79], v79 src0_sel:WORD_1
	v_pk_fma_f32 v[82:83], v[84:85], v[158:159], v[82:83]
	s_nop 0
	v_pk_fma_f32 v[78:79], v[78:79], v[162:163], v[82:83]
	v_cvt_pk_f32_fp8_e32 v[82:83], v80
	v_pk_fma_f32 v[78:79], v[82:83], v[164:165], v[78:79]
	v_cvt_pk_f32_fp8_sdwa v[82:83], v80 src0_sel:WORD_1
	v_pk_fma_f32 v[78:79], v[82:83], v[166:167], v[78:79]
	v_cvt_pk_f32_fp8_e32 v[82:83], v81
	v_cvt_pk_f32_fp8_sdwa v[80:81], v81 src0_sel:WORD_1
	v_pk_fma_f32 v[78:79], v[82:83], v[168:169], v[78:79]
	s_nop 0
	v_pk_fma_f32 v[78:79], v[80:81], v[170:171], v[78:79]
	s_waitcnt vmcnt(18)
	v_cvt_pk_f32_fp8_sdwa v[80:81], v74 src0_sel:WORD_1
	v_add_f32_e32 v82, v78, v79
	v_cvt_pk_f32_fp8_e32 v[78:79], v74
	v_pk_fma_f32 v[78:79], v[78:79], v[154:155], 0 op_sel_hi:[1,1,0]
	s_nop 0
	v_pk_fma_f32 v[78:79], v[80:81], v[156:157], v[78:79]
	v_cvt_pk_f32_fp8_e32 v[80:81], v75
	v_cvt_pk_f32_fp8_sdwa v[74:75], v75 src0_sel:WORD_1
	v_pk_fma_f32 v[78:79], v[80:81], v[158:159], v[78:79]
	s_nop 0
	v_pk_fma_f32 v[74:75], v[74:75], v[162:163], v[78:79]
	v_cvt_pk_f32_fp8_e32 v[78:79], v76
	v_pk_fma_f32 v[74:75], v[78:79], v[164:165], v[74:75]
	v_cvt_pk_f32_fp8_sdwa v[78:79], v76 src0_sel:WORD_1
	v_pk_fma_f32 v[74:75], v[78:79], v[166:167], v[74:75]
	v_cvt_pk_f32_fp8_e32 v[78:79], v77
	v_cvt_pk_f32_fp8_sdwa v[76:77], v77 src0_sel:WORD_1
	v_pk_fma_f32 v[74:75], v[78:79], v[168:169], v[74:75]
	s_nop 0
	v_pk_fma_f32 v[74:75], v[76:77], v[170:171], v[74:75]
	s_waitcnt vmcnt(17)
	v_cvt_pk_f32_fp8_sdwa v[76:77], v70 src0_sel:WORD_1
	v_add_f32_e32 v78, v74, v75
	v_cvt_pk_f32_fp8_e32 v[74:75], v70
	v_pk_fma_f32 v[74:75], v[74:75], v[154:155], 0 op_sel_hi:[1,1,0]
	s_nop 0
	v_pk_fma_f32 v[74:75], v[76:77], v[156:157], v[74:75]
	v_cvt_pk_f32_fp8_e32 v[76:77], v71
	v_cvt_pk_f32_fp8_sdwa v[70:71], v71 src0_sel:WORD_1
	v_pk_fma_f32 v[74:75], v[76:77], v[158:159], v[74:75]
	s_nop 0
	v_pk_fma_f32 v[70:71], v[70:71], v[162:163], v[74:75]
	v_cvt_pk_f32_fp8_e32 v[74:75], v72
	s_waitcnt vmcnt(15)
	v_cvt_pk_f32_fp8_e32 v[76:77], v65
	v_pk_fma_f32 v[70:71], v[74:75], v[164:165], v[70:71]
	v_cvt_pk_f32_fp8_sdwa v[74:75], v72 src0_sel:WORD_1
	v_pk_fma_f32 v[70:71], v[74:75], v[166:167], v[70:71]
	v_cvt_pk_f32_fp8_e32 v[74:75], v73
	v_cvt_pk_f32_fp8_sdwa v[72:73], v73 src0_sel:WORD_1
	v_pk_fma_f32 v[70:71], v[74:75], v[168:169], v[70:71]
	s_nop 0
	v_pk_fma_f32 v[70:71], v[72:73], v[170:171], v[70:71]
	v_cvt_pk_f32_fp8_sdwa v[72:73], v66 src0_sel:WORD_1
	v_add_f32_e32 v74, v70, v71
	v_cvt_pk_f32_fp8_e32 v[70:71], v66
	v_pk_fma_f32 v[70:71], v[70:71], v[154:155], 0 op_sel_hi:[1,1,0]
	s_nop 0
	v_pk_fma_f32 v[70:71], v[72:73], v[156:157], v[70:71]
	v_cvt_pk_f32_fp8_e32 v[72:73], v67
	v_cvt_pk_f32_fp8_sdwa v[66:67], v67 src0_sel:WORD_1
	v_pk_fma_f32 v[70:71], v[72:73], v[158:159], v[70:71]
	s_nop 0
	v_pk_fma_f32 v[66:67], v[66:67], v[162:163], v[70:71]
	v_cvt_pk_f32_fp8_e32 v[70:71], v68
	v_pk_fma_f32 v[66:67], v[70:71], v[164:165], v[66:67]
	v_cvt_pk_f32_fp8_sdwa v[70:71], v68 src0_sel:WORD_1
	v_pk_fma_f32 v[66:67], v[70:71], v[166:167], v[66:67]
	v_cvt_pk_f32_fp8_e32 v[70:71], v69
	v_cvt_pk_f32_fp8_sdwa v[68:69], v69 src0_sel:WORD_1
	v_pk_fma_f32 v[66:67], v[70:71], v[168:169], v[66:67]
	s_nop 0
	v_pk_fma_f32 v[66:67], v[68:69], v[170:171], v[66:67]
	v_add_f32_e32 v66, v66, v67
	v_cndmask_b32_e64 v127, v0, v98, s[6:7]
	v_cndmask_b32_e64 v0, v98, v0, s[6:7]
	v_cndmask_b32_e64 v128, v126, v94, s[6:7]
	v_cndmask_b32_e64 v126, v94, v126, s[6:7]
	v_cndmask_b32_e64 v129, v122, v90, s[6:7]
	v_cndmask_b32_e64 v122, v90, v122, s[6:7]
	v_cndmask_b32_e64 v123, v118, v86, s[6:7]
	v_cndmask_b32_e64 v118, v86, v118, s[6:7]
	v_cndmask_b32_e64 v124, v114, v82, s[6:7]
	v_cndmask_b32_e64 v114, v82, v114, s[6:7]
	v_cndmask_b32_e64 v125, v110, v78, s[6:7]
	v_cndmask_b32_e64 v110, v78, v110, s[6:7]
	v_cndmask_b32_e64 v119, v106, v74, s[6:7]
	v_cndmask_b32_e64 v106, v74, v106, s[6:7]
	v_cndmask_b32_e64 v120, v102, v66, s[6:7]
	v_cndmask_b32_e64 v102, v66, v102, s[6:7]
	v_add_f32_dpp v0, v127, v0 quad_perm:[1,0,3,2] row_mask:0xf bank_mask:0xf
	v_add_f32_dpp v126, v128, v126 quad_perm:[1,0,3,2] row_mask:0xf bank_mask:0xf
	v_add_f32_dpp v122, v129, v122 quad_perm:[1,0,3,2] row_mask:0xf bank_mask:0xf
	v_add_f32_dpp v118, v123, v118 quad_perm:[1,0,3,2] row_mask:0xf bank_mask:0xf
	v_add_f32_dpp v114, v124, v114 quad_perm:[1,0,3,2] row_mask:0xf bank_mask:0xf
	v_add_f32_dpp v110, v125, v110 quad_perm:[1,0,3,2] row_mask:0xf bank_mask:0xf
	v_add_f32_dpp v106, v119, v106 quad_perm:[1,0,3,2] row_mask:0xf bank_mask:0xf
	v_add_f32_dpp v102, v120, v102 quad_perm:[1,0,3,2] row_mask:0xf bank_mask:0xf
	v_cndmask_b32_e64 v127, v0, v114, s[8:9]
	v_cndmask_b32_e64 v0, v114, v0, s[8:9]
	v_cndmask_b32_e64 v128, v126, v110, s[8:9]
	v_cndmask_b32_e64 v126, v110, v126, s[8:9]
	v_cndmask_b32_e64 v129, v122, v106, s[8:9]
	v_cndmask_b32_e64 v122, v106, v122, s[8:9]
	v_cndmask_b32_e64 v123, v118, v102, s[8:9]
	v_cndmask_b32_e64 v118, v102, v118, s[8:9]
	v_add_f32_dpp v0, v127, v0 quad_perm:[2,3,0,1] row_mask:0xf bank_mask:0xf
	v_add_f32_dpp v126, v128, v126 quad_perm:[2,3,0,1] row_mask:0xf bank_mask:0xf
	v_add_f32_dpp v122, v129, v122 quad_perm:[2,3,0,1] row_mask:0xf bank_mask:0xf
	v_add_f32_dpp v118, v123, v118 quad_perm:[2,3,0,1] row_mask:0xf bank_mask:0xf
	v_cndmask_b32_e64 v127, v0, v122, s[10:11]
	v_cndmask_b32_e64 v0, v122, v0, s[10:11]
	v_cndmask_b32_e64 v128, v126, v118, s[10:11]
	v_cndmask_b32_e64 v126, v118, v126, s[10:11]
	v_mov_b32_dpp v129, v127 row_half_mirror row_mask:0xf bank_mask:0xf
	v_mov_b32_dpp v123, v128 row_half_mirror row_mask:0xf bank_mask:0xf
	s_nop 0
	v_add_f32_dpp v0, v129, v0 quad_perm:[3,2,1,0] row_mask:0xf bank_mask:0xf
	v_add_f32_dpp v126, v123, v126 quad_perm:[3,2,1,0] row_mask:0xf bank_mask:0xf
	v_cndmask_b32_e64 v127, v0, v126, s[12:13]
	v_cndmask_b32_e64 v0, v126, v0, s[12:13]
	s_nop 1
	v_add_f32_dpp v0, v127, v0 row_ror:8 row_mask:0xf bank_mask:0xf
	s_waitcnt vmcnt(14)
	v_cvt_pk_f32_fp8_e32 v[78:79], v58
	v_cvt_pk_f32_fp8_sdwa v[74:75], v64 src0_sel:WORD_1
	ds_bpermute_b32 v66, v214, v0
	s_waitcnt lgkmcnt(0)
	v_add_f32_e32 v0, v0, v66
	ds_bpermute_b32 v66, v215, v0
	s_waitcnt lgkmcnt(0)
	v_add_f32_e32 v0, v0, v66
	v_add_u32_e32 v66, s1, v151
	ds_read2st64_b32 v[66:67], v66 offset1:2
	s_waitcnt lgkmcnt(0)
	v_mul_f32_e32 v0, v66, v0
	v_mul_f32_e32 v66, 0x3d372713, v0
	v_mul_f32_e32 v66, v0, v66
	v_fma_f32 v66, v0, v66, v0
	v_mul_f32_e32 v66, 0xbfcc422a, v66
	v_mul_f32_e32 v66, 0x3fb8aa3b, v66
	v_exp_f32_e32 v66, v66
	s_nop 0
	v_add_f32_e32 v66, 1.0, v66
	v_div_scale_f32 v68, s[42:43], v66, v66, v0
	v_rcp_f32_e32 v69, v68
	s_nop 0
	v_fma_f32 v70, -v68, v69, 1.0
	v_fmac_f32_e32 v69, v70, v69
	v_div_scale_f32 v70, vcc, v0, v66, v0
	v_mul_f32_e32 v71, v70, v69
	v_fma_f32 v72, -v68, v71, v70
	v_fmac_f32_e32 v71, v72, v69
	v_fma_f32 v68, -v68, v71, v70
	v_div_fmas_f32 v68, v68, v69, v71
	v_div_fixup_f32 v0, v68, v66, v0
	v_mul_f32_e32 v0, v67, v0
	v_cvt_pk_f32_fp8_e32 v[66:67], v62
	v_cvt_pk_f32_fp8_sdwa v[68:69], v62 src0_sel:WORD_1
	v_cvt_pk_f32_fp8_e32 v[70:71], v63
	v_cvt_pk_f32_fp8_sdwa v[62:63], v63 src0_sel:WORD_1
	v_cvt_pk_f32_fp8_e32 v[72:73], v64
	v_cvt_pk_f32_fp8_sdwa v[64:65], v65 src0_sel:WORD_1
	v_readlane_b32 s0, v0, 0
	s_nop 1
	v_pk_fma_f32 v[66:67], v[66:67], s[0:1], v[184:185] op_sel_hi:[1,0,1]
	v_pk_fma_f32 v[68:69], v[68:69], s[0:1], v[186:187] op_sel_hi:[1,0,1]
	v_pk_fma_f32 v[70:71], v[70:71], s[0:1], v[182:183] op_sel_hi:[1,0,1]
	v_pk_fma_f32 v[62:63], v[62:63], s[0:1], v[180:181] op_sel_hi:[1,0,1]
	v_pk_fma_f32 v[72:73], v[72:73], s[0:1], v[178:179] op_sel_hi:[1,0,1]
	v_pk_fma_f32 v[74:75], v[74:75], s[0:1], v[176:177] op_sel_hi:[1,0,1]
	v_pk_fma_f32 v[76:77], v[76:77], s[0:1], v[174:175] op_sel_hi:[1,0,1]
	v_pk_fma_f32 v[64:65], v[64:65], s[0:1], v[172:173] op_sel_hi:[1,0,1]
	v_readlane_b32 s0, v0, 8
	s_nop 1
	v_pk_fma_f32 v[66:67], v[78:79], s[0:1], v[66:67] op_sel_hi:[1,0,1]
	v_cvt_pk_f32_fp8_sdwa v[78:79], v58 src0_sel:WORD_1
	v_pk_fma_f32 v[68:69], v[78:79], s[0:1], v[68:69] op_sel_hi:[1,0,1]
	v_cvt_pk_f32_fp8_e32 v[78:79], v59
	v_cvt_pk_f32_fp8_sdwa v[58:59], v59 src0_sel:WORD_1
	v_pk_fma_f32 v[70:71], v[78:79], s[0:1], v[70:71] op_sel_hi:[1,0,1]
	v_pk_fma_f32 v[58:59], v[58:59], s[0:1], v[62:63] op_sel_hi:[1,0,1]
	v_cvt_pk_f32_fp8_e32 v[62:63], v60
	v_pk_fma_f32 v[62:63], v[62:63], s[0:1], v[72:73] op_sel_hi:[1,0,1]
	v_cvt_pk_f32_fp8_sdwa v[72:73], v60 src0_sel:WORD_1
	v_pk_fma_f32 v[72:73], v[72:73], s[0:1], v[74:75] op_sel_hi:[1,0,1]
	v_cvt_pk_f32_fp8_e32 v[74:75], v61
	v_cvt_pk_f32_fp8_sdwa v[60:61], v61 src0_sel:WORD_1
	v_pk_fma_f32 v[74:75], v[74:75], s[0:1], v[76:77] op_sel_hi:[1,0,1]
	v_pk_fma_f32 v[60:61], v[60:61], s[0:1], v[64:65] op_sel_hi:[1,0,1]
	s_waitcnt vmcnt(13)
	v_cvt_pk_f32_fp8_e32 v[64:65], v54
	v_readlane_b32 s0, v0, 4
	s_nop 1
	v_pk_fma_f32 v[64:65], v[64:65], s[0:1], v[66:67] op_sel_hi:[1,0,1]
	v_cvt_pk_f32_fp8_sdwa v[66:67], v54 src0_sel:WORD_1
	v_pk_fma_f32 v[66:67], v[66:67], s[0:1], v[68:69] op_sel_hi:[1,0,1]
	v_cvt_pk_f32_fp8_e32 v[68:69], v55
	v_cvt_pk_f32_fp8_sdwa v[54:55], v55 src0_sel:WORD_1
	v_pk_fma_f32 v[68:69], v[68:69], s[0:1], v[70:71] op_sel_hi:[1,0,1]
	v_pk_fma_f32 v[54:55], v[54:55], s[0:1], v[58:59] op_sel_hi:[1,0,1]
	v_cvt_pk_f32_fp8_e32 v[58:59], v56
	v_cvt_pk_f32_fp8_e32 v[70:71], v57
	v_pk_fma_f32 v[58:59], v[58:59], s[0:1], v[62:63] op_sel_hi:[1,0,1]
	v_cvt_pk_f32_fp8_sdwa v[62:63], v56 src0_sel:WORD_1
	v_cvt_pk_f32_fp8_sdwa v[56:57], v57 src0_sel:WORD_1
	v_pk_fma_f32 v[70:71], v[70:71], s[0:1], v[74:75] op_sel_hi:[1,0,1]
	v_pk_fma_f32 v[62:63], v[62:63], s[0:1], v[72:73] op_sel_hi:[1,0,1]
	v_pk_fma_f32 v[56:57], v[56:57], s[0:1], v[60:61] op_sel_hi:[1,0,1]
	s_waitcnt vmcnt(12)
	v_cvt_pk_f32_fp8_e32 v[60:61], v50
	v_readlane_b32 s0, v0, 12
	s_nop 1
	v_pk_fma_f32 v[60:61], v[60:61], s[0:1], v[64:65] op_sel_hi:[1,0,1]
	v_cvt_pk_f32_fp8_sdwa v[64:65], v50 src0_sel:WORD_1
	v_pk_fma_f32 v[64:65], v[64:65], s[0:1], v[66:67] op_sel_hi:[1,0,1]
	v_cvt_pk_f32_fp8_e32 v[66:67], v51
	v_cvt_pk_f32_fp8_sdwa v[50:51], v51 src0_sel:WORD_1
	v_pk_fma_f32 v[66:67], v[66:67], s[0:1], v[68:69] op_sel_hi:[1,0,1]
	v_pk_fma_f32 v[50:51], v[50:51], s[0:1], v[54:55] op_sel_hi:[1,0,1]
	v_cvt_pk_f32_fp8_e32 v[54:55], v52
	v_pk_fma_f32 v[54:55], v[54:55], s[0:1], v[58:59] op_sel_hi:[1,0,1]
	v_cvt_pk_f32_fp8_sdwa v[58:59], v52 src0_sel:WORD_1
	v_pk_fma_f32 v[58:59], v[58:59], s[0:1], v[62:63] op_sel_hi:[1,0,1]
	v_cvt_pk_f32_fp8_e32 v[62:63], v53
	v_cvt_pk_f32_fp8_sdwa v[52:53], v53 src0_sel:WORD_1
	v_pk_fma_f32 v[62:63], v[62:63], s[0:1], v[70:71] op_sel_hi:[1,0,1]
	v_pk_fma_f32 v[52:53], v[52:53], s[0:1], v[56:57] op_sel_hi:[1,0,1]
	s_waitcnt vmcnt(11)
	v_cvt_pk_f32_fp8_e32 v[56:57], v46
	v_readlane_b32 s0, v0, 2
	s_nop 1
	v_pk_fma_f32 v[56:57], v[56:57], s[0:1], v[60:61] op_sel_hi:[1,0,1]
	v_cvt_pk_f32_fp8_sdwa v[60:61], v46 src0_sel:WORD_1
	v_pk_fma_f32 v[60:61], v[60:61], s[0:1], v[64:65] op_sel_hi:[1,0,1]
	v_cvt_pk_f32_fp8_e32 v[64:65], v47
	v_cvt_pk_f32_fp8_sdwa v[46:47], v47 src0_sel:WORD_1
	v_pk_fma_f32 v[64:65], v[64:65], s[0:1], v[66:67] op_sel_hi:[1,0,1]
	v_pk_fma_f32 v[46:47], v[46:47], s[0:1], v[50:51] op_sel_hi:[1,0,1]
	v_cvt_pk_f32_fp8_e32 v[50:51], v48
	v_pk_fma_f32 v[50:51], v[50:51], s[0:1], v[54:55] op_sel_hi:[1,0,1]
	v_cvt_pk_f32_fp8_sdwa v[54:55], v48 src0_sel:WORD_1
	v_pk_fma_f32 v[54:55], v[54:55], s[0:1], v[58:59] op_sel_hi:[1,0,1]
	v_cvt_pk_f32_fp8_e32 v[58:59], v49
	v_cvt_pk_f32_fp8_sdwa v[48:49], v49 src0_sel:WORD_1
	v_pk_fma_f32 v[58:59], v[58:59], s[0:1], v[62:63] op_sel_hi:[1,0,1]
	v_pk_fma_f32 v[48:49], v[48:49], s[0:1], v[52:53] op_sel_hi:[1,0,1]
	s_waitcnt vmcnt(10)
	v_cvt_pk_f32_fp8_e32 v[52:53], v42
	v_readlane_b32 s0, v0, 10
	s_nop 1
	v_pk_fma_f32 v[52:53], v[52:53], s[0:1], v[56:57] op_sel_hi:[1,0,1]
	v_cvt_pk_f32_fp8_sdwa v[56:57], v42 src0_sel:WORD_1
	v_pk_fma_f32 v[56:57], v[56:57], s[0:1], v[60:61] op_sel_hi:[1,0,1]
	v_cvt_pk_f32_fp8_e32 v[60:61], v43
	v_cvt_pk_f32_fp8_sdwa v[42:43], v43 src0_sel:WORD_1
	v_pk_fma_f32 v[60:61], v[60:61], s[0:1], v[64:65] op_sel_hi:[1,0,1]
	v_pk_fma_f32 v[42:43], v[42:43], s[0:1], v[46:47] op_sel_hi:[1,0,1]
	v_cvt_pk_f32_fp8_e32 v[46:47], v44
	v_pk_fma_f32 v[46:47], v[46:47], s[0:1], v[50:51] op_sel_hi:[1,0,1]
	v_cvt_pk_f32_fp8_sdwa v[50:51], v44 src0_sel:WORD_1
	v_pk_fma_f32 v[50:51], v[50:51], s[0:1], v[54:55] op_sel_hi:[1,0,1]
	v_cvt_pk_f32_fp8_e32 v[54:55], v45
	v_cvt_pk_f32_fp8_sdwa v[44:45], v45 src0_sel:WORD_1
	v_pk_fma_f32 v[54:55], v[54:55], s[0:1], v[58:59] op_sel_hi:[1,0,1]
	v_pk_fma_f32 v[44:45], v[44:45], s[0:1], v[48:49] op_sel_hi:[1,0,1]
	s_waitcnt vmcnt(9)
	v_cvt_pk_f32_fp8_e32 v[48:49], v38
	v_readlane_b32 s0, v0, 6
	s_nop 1
	v_pk_fma_f32 v[48:49], v[48:49], s[0:1], v[52:53] op_sel_hi:[1,0,1]
	v_cvt_pk_f32_fp8_sdwa v[52:53], v38 src0_sel:WORD_1
	v_pk_fma_f32 v[52:53], v[52:53], s[0:1], v[56:57] op_sel_hi:[1,0,1]
	v_cvt_pk_f32_fp8_e32 v[56:57], v39
	v_cvt_pk_f32_fp8_sdwa v[38:39], v39 src0_sel:WORD_1
	v_pk_fma_f32 v[56:57], v[56:57], s[0:1], v[60:61] op_sel_hi:[1,0,1]
	v_pk_fma_f32 v[38:39], v[38:39], s[0:1], v[42:43] op_sel_hi:[1,0,1]
	v_cvt_pk_f32_fp8_e32 v[42:43], v40
	v_pk_fma_f32 v[42:43], v[42:43], s[0:1], v[46:47] op_sel_hi:[1,0,1]
	v_cvt_pk_f32_fp8_sdwa v[46:47], v40 src0_sel:WORD_1
	v_pk_fma_f32 v[46:47], v[46:47], s[0:1], v[50:51] op_sel_hi:[1,0,1]
	v_cvt_pk_f32_fp8_e32 v[50:51], v41
	v_cvt_pk_f32_fp8_sdwa v[40:41], v41 src0_sel:WORD_1
	v_pk_fma_f32 v[50:51], v[50:51], s[0:1], v[54:55] op_sel_hi:[1,0,1]
	v_pk_fma_f32 v[40:41], v[40:41], s[0:1], v[44:45] op_sel_hi:[1,0,1]
	s_waitcnt vmcnt(8)
	v_cvt_pk_f32_fp8_e32 v[44:45], v34
	v_readlane_b32 s0, v0, 14
	s_nop 1
	v_pk_fma_f32 v[44:45], v[44:45], s[0:1], v[48:49] op_sel_hi:[1,0,1]
	v_cvt_pk_f32_fp8_sdwa v[48:49], v34 src0_sel:WORD_1
	v_pk_fma_f32 v[48:49], v[48:49], s[0:1], v[52:53] op_sel_hi:[1,0,1]
	v_cvt_pk_f32_fp8_e32 v[52:53], v35
	v_cvt_pk_f32_fp8_sdwa v[34:35], v35 src0_sel:WORD_1
	v_pk_fma_f32 v[52:53], v[52:53], s[0:1], v[56:57] op_sel_hi:[1,0,1]
	v_pk_fma_f32 v[34:35], v[34:35], s[0:1], v[38:39] op_sel_hi:[1,0,1]
	v_cvt_pk_f32_fp8_e32 v[38:39], v36
	v_pk_fma_f32 v[38:39], v[38:39], s[0:1], v[42:43] op_sel_hi:[1,0,1]
	v_cvt_pk_f32_fp8_sdwa v[42:43], v36 src0_sel:WORD_1
	v_pk_fma_f32 v[42:43], v[42:43], s[0:1], v[46:47] op_sel_hi:[1,0,1]
	v_cvt_pk_f32_fp8_e32 v[46:47], v37
	v_cvt_pk_f32_fp8_sdwa v[36:37], v37 src0_sel:WORD_1
	v_pk_fma_f32 v[46:47], v[46:47], s[0:1], v[50:51] op_sel_hi:[1,0,1]
	v_pk_fma_f32 v[36:37], v[36:37], s[0:1], v[40:41] op_sel_hi:[1,0,1]
	s_waitcnt vmcnt(7)
	v_cvt_pk_f32_fp8_e32 v[40:41], v30
	v_readlane_b32 s0, v0, 1
	s_nop 1
	v_pk_fma_f32 v[40:41], v[40:41], s[0:1], v[44:45] op_sel_hi:[1,0,1]
	v_cvt_pk_f32_fp8_sdwa v[44:45], v30 src0_sel:WORD_1
	v_pk_fma_f32 v[44:45], v[44:45], s[0:1], v[48:49] op_sel_hi:[1,0,1]
	v_cvt_pk_f32_fp8_e32 v[48:49], v31
	v_cvt_pk_f32_fp8_sdwa v[30:31], v31 src0_sel:WORD_1
	v_pk_fma_f32 v[48:49], v[48:49], s[0:1], v[52:53] op_sel_hi:[1,0,1]
	v_pk_fma_f32 v[30:31], v[30:31], s[0:1], v[34:35] op_sel_hi:[1,0,1]
	v_cvt_pk_f32_fp8_e32 v[34:35], v32
	v_pk_fma_f32 v[34:35], v[34:35], s[0:1], v[38:39] op_sel_hi:[1,0,1]
	v_cvt_pk_f32_fp8_sdwa v[38:39], v32 src0_sel:WORD_1
	v_pk_fma_f32 v[38:39], v[38:39], s[0:1], v[42:43] op_sel_hi:[1,0,1]
	v_cvt_pk_f32_fp8_e32 v[42:43], v33
	v_cvt_pk_f32_fp8_sdwa v[32:33], v33 src0_sel:WORD_1
	v_pk_fma_f32 v[42:43], v[42:43], s[0:1], v[46:47] op_sel_hi:[1,0,1]
	v_pk_fma_f32 v[32:33], v[32:33], s[0:1], v[36:37] op_sel_hi:[1,0,1]
	s_waitcnt vmcnt(6)
	v_cvt_pk_f32_fp8_e32 v[36:37], v26
	v_readlane_b32 s0, v0, 9
	s_nop 1
	v_pk_fma_f32 v[36:37], v[36:37], s[0:1], v[40:41] op_sel_hi:[1,0,1]
	v_cvt_pk_f32_fp8_sdwa v[40:41], v26 src0_sel:WORD_1
	v_pk_fma_f32 v[40:41], v[40:41], s[0:1], v[44:45] op_sel_hi:[1,0,1]
	v_cvt_pk_f32_fp8_e32 v[44:45], v27
	v_cvt_pk_f32_fp8_sdwa v[26:27], v27 src0_sel:WORD_1
	v_pk_fma_f32 v[44:45], v[44:45], s[0:1], v[48:49] op_sel_hi:[1,0,1]
	v_pk_fma_f32 v[26:27], v[26:27], s[0:1], v[30:31] op_sel_hi:[1,0,1]
	v_cvt_pk_f32_fp8_e32 v[30:31], v28
	v_pk_fma_f32 v[30:31], v[30:31], s[0:1], v[34:35] op_sel_hi:[1,0,1]
	v_cvt_pk_f32_fp8_sdwa v[34:35], v28 src0_sel:WORD_1
	v_pk_fma_f32 v[34:35], v[34:35], s[0:1], v[38:39] op_sel_hi:[1,0,1]
	v_cvt_pk_f32_fp8_e32 v[38:39], v29
	v_cvt_pk_f32_fp8_sdwa v[28:29], v29 src0_sel:WORD_1
	v_pk_fma_f32 v[38:39], v[38:39], s[0:1], v[42:43] op_sel_hi:[1,0,1]
	v_pk_fma_f32 v[28:29], v[28:29], s[0:1], v[32:33] op_sel_hi:[1,0,1]
	s_waitcnt vmcnt(5)
	v_cvt_pk_f32_fp8_e32 v[32:33], v22
	v_readlane_b32 s0, v0, 5
	s_nop 1
	v_pk_fma_f32 v[32:33], v[32:33], s[0:1], v[36:37] op_sel_hi:[1,0,1]
	v_cvt_pk_f32_fp8_sdwa v[36:37], v22 src0_sel:WORD_1
	v_pk_fma_f32 v[36:37], v[36:37], s[0:1], v[40:41] op_sel_hi:[1,0,1]
	v_cvt_pk_f32_fp8_e32 v[40:41], v23
	v_cvt_pk_f32_fp8_sdwa v[22:23], v23 src0_sel:WORD_1
	v_pk_fma_f32 v[40:41], v[40:41], s[0:1], v[44:45] op_sel_hi:[1,0,1]
	v_pk_fma_f32 v[22:23], v[22:23], s[0:1], v[26:27] op_sel_hi:[1,0,1]
	v_cvt_pk_f32_fp8_e32 v[26:27], v24
	v_pk_fma_f32 v[26:27], v[26:27], s[0:1], v[30:31] op_sel_hi:[1,0,1]
	v_cvt_pk_f32_fp8_sdwa v[30:31], v24 src0_sel:WORD_1
	v_pk_fma_f32 v[30:31], v[30:31], s[0:1], v[34:35] op_sel_hi:[1,0,1]
	v_cvt_pk_f32_fp8_e32 v[34:35], v25
	v_cvt_pk_f32_fp8_sdwa v[24:25], v25 src0_sel:WORD_1
	v_pk_fma_f32 v[34:35], v[34:35], s[0:1], v[38:39] op_sel_hi:[1,0,1]
	v_pk_fma_f32 v[24:25], v[24:25], s[0:1], v[28:29] op_sel_hi:[1,0,1]
	s_waitcnt vmcnt(4)
	v_cvt_pk_f32_fp8_e32 v[28:29], v18
	v_readlane_b32 s0, v0, 13
	s_nop 1
	v_pk_fma_f32 v[28:29], v[28:29], s[0:1], v[32:33] op_sel_hi:[1,0,1]
	v_cvt_pk_f32_fp8_sdwa v[32:33], v18 src0_sel:WORD_1
	v_pk_fma_f32 v[32:33], v[32:33], s[0:1], v[36:37] op_sel_hi:[1,0,1]
	v_cvt_pk_f32_fp8_e32 v[36:37], v19
	v_cvt_pk_f32_fp8_sdwa v[18:19], v19 src0_sel:WORD_1
	v_pk_fma_f32 v[36:37], v[36:37], s[0:1], v[40:41] op_sel_hi:[1,0,1]
	v_pk_fma_f32 v[18:19], v[18:19], s[0:1], v[22:23] op_sel_hi:[1,0,1]
	v_cvt_pk_f32_fp8_e32 v[22:23], v20
	v_pk_fma_f32 v[22:23], v[22:23], s[0:1], v[26:27] op_sel_hi:[1,0,1]
	v_cvt_pk_f32_fp8_sdwa v[26:27], v20 src0_sel:WORD_1
	v_pk_fma_f32 v[26:27], v[26:27], s[0:1], v[30:31] op_sel_hi:[1,0,1]
	v_cvt_pk_f32_fp8_e32 v[30:31], v21
	v_cvt_pk_f32_fp8_sdwa v[20:21], v21 src0_sel:WORD_1
	v_pk_fma_f32 v[30:31], v[30:31], s[0:1], v[34:35] op_sel_hi:[1,0,1]
	v_pk_fma_f32 v[20:21], v[20:21], s[0:1], v[24:25] op_sel_hi:[1,0,1]
	s_waitcnt vmcnt(3)
	v_cvt_pk_f32_fp8_e32 v[24:25], v14
	v_readlane_b32 s0, v0, 3
	s_nop 1
	v_pk_fma_f32 v[24:25], v[24:25], s[0:1], v[28:29] op_sel_hi:[1,0,1]
	v_cvt_pk_f32_fp8_sdwa v[28:29], v14 src0_sel:WORD_1
	v_pk_fma_f32 v[28:29], v[28:29], s[0:1], v[32:33] op_sel_hi:[1,0,1]
	v_cvt_pk_f32_fp8_e32 v[32:33], v15
	v_cvt_pk_f32_fp8_sdwa v[14:15], v15 src0_sel:WORD_1
	v_pk_fma_f32 v[32:33], v[32:33], s[0:1], v[36:37] op_sel_hi:[1,0,1]
	v_pk_fma_f32 v[14:15], v[14:15], s[0:1], v[18:19] op_sel_hi:[1,0,1]
	v_cvt_pk_f32_fp8_e32 v[18:19], v16
	v_pk_fma_f32 v[18:19], v[18:19], s[0:1], v[22:23] op_sel_hi:[1,0,1]
	v_cvt_pk_f32_fp8_sdwa v[22:23], v16 src0_sel:WORD_1
	v_pk_fma_f32 v[22:23], v[22:23], s[0:1], v[26:27] op_sel_hi:[1,0,1]
	v_cvt_pk_f32_fp8_e32 v[26:27], v17
	v_cvt_pk_f32_fp8_sdwa v[16:17], v17 src0_sel:WORD_1
	v_pk_fma_f32 v[26:27], v[26:27], s[0:1], v[30:31] op_sel_hi:[1,0,1]
	v_pk_fma_f32 v[16:17], v[16:17], s[0:1], v[20:21] op_sel_hi:[1,0,1]
	s_waitcnt vmcnt(2)
	v_cvt_pk_f32_fp8_e32 v[20:21], v10
	v_readlane_b32 s0, v0, 11
	s_nop 1
	v_pk_fma_f32 v[20:21], v[20:21], s[0:1], v[24:25] op_sel_hi:[1,0,1]
	v_cvt_pk_f32_fp8_sdwa v[24:25], v10 src0_sel:WORD_1
	v_pk_fma_f32 v[24:25], v[24:25], s[0:1], v[28:29] op_sel_hi:[1,0,1]
	v_cvt_pk_f32_fp8_e32 v[28:29], v11
	v_cvt_pk_f32_fp8_sdwa v[10:11], v11 src0_sel:WORD_1
	v_pk_fma_f32 v[28:29], v[28:29], s[0:1], v[32:33] op_sel_hi:[1,0,1]
	v_pk_fma_f32 v[10:11], v[10:11], s[0:1], v[14:15] op_sel_hi:[1,0,1]
	v_cvt_pk_f32_fp8_e32 v[14:15], v12
	v_pk_fma_f32 v[14:15], v[14:15], s[0:1], v[18:19] op_sel_hi:[1,0,1]
	v_cvt_pk_f32_fp8_sdwa v[18:19], v12 src0_sel:WORD_1
	v_pk_fma_f32 v[18:19], v[18:19], s[0:1], v[22:23] op_sel_hi:[1,0,1]
	v_cvt_pk_f32_fp8_e32 v[22:23], v13
	v_cvt_pk_f32_fp8_sdwa v[12:13], v13 src0_sel:WORD_1
	v_pk_fma_f32 v[22:23], v[22:23], s[0:1], v[26:27] op_sel_hi:[1,0,1]
	v_pk_fma_f32 v[12:13], v[12:13], s[0:1], v[16:17] op_sel_hi:[1,0,1]
	s_waitcnt vmcnt(1)
	v_cvt_pk_f32_fp8_e32 v[16:17], v6
	v_readlane_b32 s0, v0, 7
	s_nop 1
	v_pk_fma_f32 v[16:17], v[16:17], s[0:1], v[20:21] op_sel_hi:[1,0,1]
	v_cvt_pk_f32_fp8_sdwa v[20:21], v6 src0_sel:WORD_1
	v_pk_fma_f32 v[20:21], v[20:21], s[0:1], v[24:25] op_sel_hi:[1,0,1]
	v_cvt_pk_f32_fp8_e32 v[24:25], v7
	v_cvt_pk_f32_fp8_sdwa v[6:7], v7 src0_sel:WORD_1
	v_pk_fma_f32 v[24:25], v[24:25], s[0:1], v[28:29] op_sel_hi:[1,0,1]
	v_pk_fma_f32 v[6:7], v[6:7], s[0:1], v[10:11] op_sel_hi:[1,0,1]
	v_cvt_pk_f32_fp8_e32 v[10:11], v8
	v_pk_fma_f32 v[10:11], v[10:11], s[0:1], v[14:15] op_sel_hi:[1,0,1]
	v_cvt_pk_f32_fp8_sdwa v[14:15], v8 src0_sel:WORD_1
	v_pk_fma_f32 v[14:15], v[14:15], s[0:1], v[18:19] op_sel_hi:[1,0,1]
	v_cvt_pk_f32_fp8_e32 v[18:19], v9
	v_cvt_pk_f32_fp8_sdwa v[8:9], v9 src0_sel:WORD_1
	v_pk_fma_f32 v[18:19], v[18:19], s[0:1], v[22:23] op_sel_hi:[1,0,1]
	v_pk_fma_f32 v[8:9], v[8:9], s[0:1], v[12:13] op_sel_hi:[1,0,1]
	s_waitcnt vmcnt(0)
	v_cvt_pk_f32_fp8_e32 v[12:13], v2
	v_readlane_b32 s0, v0, 15
	s_nop 1
	v_pk_fma_f32 v[184:185], v[12:13], s[0:1], v[16:17] op_sel_hi:[1,0,1]
	v_cvt_pk_f32_fp8_sdwa v[12:13], v2 src0_sel:WORD_1
	v_pk_fma_f32 v[186:187], v[12:13], s[0:1], v[20:21] op_sel_hi:[1,0,1]
	v_cvt_pk_f32_fp8_e32 v[12:13], v3
	v_cvt_pk_f32_fp8_sdwa v[2:3], v3 src0_sel:WORD_1
	v_pk_fma_f32 v[182:183], v[12:13], s[0:1], v[24:25] op_sel_hi:[1,0,1]
	v_pk_fma_f32 v[180:181], v[2:3], s[0:1], v[6:7] op_sel_hi:[1,0,1]
	v_cvt_pk_f32_fp8_e32 v[2:3], v4
	v_pk_fma_f32 v[178:179], v[2:3], s[0:1], v[10:11] op_sel_hi:[1,0,1]
	v_cvt_pk_f32_fp8_sdwa v[2:3], v4 src0_sel:WORD_1
	v_pk_fma_f32 v[176:177], v[2:3], s[0:1], v[14:15] op_sel_hi:[1,0,1]
	v_cvt_pk_f32_fp8_e32 v[2:3], v5
	v_pk_fma_f32 v[174:175], v[2:3], s[0:1], v[18:19] op_sel_hi:[1,0,1]
	v_cvt_pk_f32_fp8_sdwa v[2:3], v5 src0_sel:WORD_1
	v_pk_fma_f32 v[172:173], v[2:3], s[0:1], v[8:9] op_sel_hi:[1,0,1]
	s_add_i32 s1, s1, 64
	s_cmpk_lg_i32 s1, 0x200
	s_cbranch_scc1 .LBB0_870
	v_add_u32_e32 v0, 0xfffff000, v152
	v_lshrrev_b32_e32 v0, 10, v0
	v_add_u32_e32 v0, 1, v0
	v_cmp_lt_i32_e32 vcc, s57, v152
	v_mov_b64_e32 v[2:3], s[16:17]
	v_lshlrev_b64 v[4:5], 12, v[152:153]
	v_cndmask_b32_e32 v0, 0, v0, vcc
	v_add_u32_e32 v46, s40, v0
	v_mad_u64_u32 v[2:3], s[0:1], v46, s63, v[2:3]
	v_lshlrev_b32_e32 v0, 2, v136
	v_lshl_add_u64 v[2:3], v[2:3], 0, v[0:1]
	s_mov_b64 s[0:1], 0x5000
	v_lshl_add_u64 v[52:53], v[2:3], 0, s[0:1]
	s_movk_i32 s0, 0x5000
	v_lshl_add_u64 v[40:41], v[142:143], 0, v[4:5]
	v_add_co_u32_e32 v2, vcc, s0, v2
	global_load_dwordx4 v[10:13], v[40:41], off
	s_nop 0
	v_addc_co_u32_e32 v3, vcc, 0, v3, vcc
	global_load_dwordx4 v[16:19], v[2:3], off
	s_nop 0
	global_load_dwordx4 v[2:5], v[146:147], off
	global_load_dwordx4 v[6:9], v[148:149], off
	v_lshlrev_b64 v[38:39], 10, v[152:153]
	s_mov_b64 s[0:1], -1
	s_waitcnt vmcnt(2)
	v_pk_mul_f32 v[14:15], v[184:185], v[16:17]
	s_nop 0
	v_pk_fma_f32 v[16:17], v[10:11], s[86:87], v[14:15] op_sel_hi:[1,0,1]
	s_nop 0
	v_add_f32_e32 v10, 0, v16
	v_add_f32_e32 v20, v17, v10
	v_pk_mul_f32 v[10:11], v[186:187], v[18:19]
	s_nop 0
	v_pk_fma_f32 v[14:15], v[12:13], s[86:87], v[10:11] op_sel_hi:[1,0,1]
	s_nop 0
	v_add_f32_e32 v10, v14, v20
	v_add_f32_e32 v30, v15, v10
	global_load_dwordx4 v[22:25], v[40:41], off offset:1024
	global_load_dwordx4 v[26:29], v[52:53], off offset:1024
	global_load_dwordx4 v[10:13], v[146:147], off offset:1024
	global_load_dwordx4 v[18:21], v[148:149], off offset:1024
	s_waitcnt vmcnt(2)
	v_pk_mul_f32 v[26:27], v[182:183], v[26:27]
	s_nop 0
	v_pk_fma_f32 v[44:45], v[22:23], s[86:87], v[26:27] op_sel_hi:[1,0,1]
	s_nop 0
	v_add_f32_e32 v22, v44, v30
	v_add_f32_e32 v26, v45, v22
	v_pk_mul_f32 v[22:23], v[180:181], v[28:29]
	s_nop 0
	v_pk_fma_f32 v[42:43], v[24:25], s[86:87], v[22:23] op_sel_hi:[1,0,1]
	s_nop 0
	v_add_f32_e32 v22, v42, v26
	v_add_f32_e32 v47, v43, v22
	global_load_dwordx4 v[30:33], v[40:41], off offset:2048
	global_load_dwordx4 v[34:37], v[52:53], off offset:2048
	global_load_dwordx4 v[22:25], v[146:147], off offset:2048
	global_load_dwordx4 v[26:29], v[148:149], off offset:2048
	s_waitcnt vmcnt(2)
	v_pk_mul_f32 v[34:35], v[178:179], v[34:35]
	s_nop 0
	v_pk_fma_f32 v[56:57], v[30:31], s[86:87], v[34:35] op_sel_hi:[1,0,1]
	s_nop 0
	v_add_f32_e32 v30, v56, v47
	v_add_f32_e32 v34, v57, v30
	v_pk_mul_f32 v[30:31], v[176:177], v[36:37]
	s_nop 0
	v_pk_fma_f32 v[58:59], v[32:33], s[86:87], v[30:31] op_sel_hi:[1,0,1]
	s_nop 0
	v_add_f32_e32 v30, v58, v34
	v_add_f32_e32 v47, v59, v30
	global_load_dwordx4 v[48:51], v[40:41], off offset:3072
	s_nop 0
	global_load_dwordx4 v[52:55], v[52:53], off offset:3072
	s_nop 0
	global_load_dwordx4 v[30:33], v[146:147], off offset:3072
	global_load_dwordx4 v[34:37], v[148:149], off offset:3072
	s_waitcnt vmcnt(2)
	v_pk_mul_f32 v[52:53], v[174:175], v[52:53]
	s_nop 0
	v_pk_fma_f32 v[48:49], v[48:49], s[86:87], v[52:53] op_sel_hi:[1,0,1]
	v_pk_mul_f32 v[52:53], v[172:173], v[54:55]
	v_add_f32_e32 v47, v48, v47
	v_add_f32_e32 v47, v49, v47
	v_pk_fma_f32 v[50:51], v[50:51], s[86:87], v[52:53] op_sel_hi:[1,0,1]
	s_nop 0
	v_add_f32_e32 v47, v50, v47
	v_add_f32_e32 v47, v51, v47
	ds_bpermute_b32 v52, v215, v47
	s_waitcnt lgkmcnt(0)
	v_add_f32_e32 v47, v47, v52
	ds_bpermute_b32 v52, v214, v47
	s_waitcnt lgkmcnt(0)
	v_add_f32_e32 v47, v47, v52
	s_waitcnt lgkmcnt(0)
	s_nop 1
	v_add_f32_dpp v47, v47, v47 row_ror:8 row_mask:0xf bank_mask:0xf
	s_waitcnt lgkmcnt(0)
	s_nop 1
	v_mov_b32_dpp v52, v47 row_half_mirror row_mask:0xf bank_mask:0xf
	s_nop 1
	v_add_f32_dpp v47, v52, v47 quad_perm:[3,2,1,0] row_mask:0xf bank_mask:0xf
	s_waitcnt lgkmcnt(0)
	s_nop 1
	v_add_f32_dpp v47, v47, v47 quad_perm:[2,3,0,1] row_mask:0xf bank_mask:0xf
	s_waitcnt lgkmcnt(0)
	s_nop 1
	v_add_f32_dpp v47, v47, v47 quad_perm:[1,0,3,2] row_mask:0xf bank_mask:0xf
	v_mul_f32_e32 v52, 0x3a800000, v47
	v_pk_add_f32 v[16:17], v[16:17], v[52:53] op_sel_hi:[1,0] neg_lo:[0,1] neg_hi:[0,1]
	v_pk_add_f32 v[60:61], v[14:15], v[52:53] op_sel_hi:[1,0] neg_lo:[0,1] neg_hi:[0,1]
	v_pk_mul_f32 v[54:55], v[16:17], v[16:17]
	v_pk_mul_f32 v[14:15], v[60:61], v[60:61]
	v_add_f32_e32 v47, v54, v55
	v_pk_add_f32 v[44:45], v[44:45], v[52:53] op_sel_hi:[1,0] neg_lo:[0,1] neg_hi:[0,1]
	v_add_f32_e32 v14, v14, v47
	v_pk_mul_f32 v[62:63], v[44:45], v[44:45]
	v_add_f32_e32 v14, v15, v14
	v_pk_add_f32 v[42:43], v[42:43], v[52:53] op_sel_hi:[1,0] neg_lo:[0,1] neg_hi:[0,1]
	v_add_f32_e32 v14, v62, v14
	v_pk_mul_f32 v[64:65], v[42:43], v[42:43]
	v_add_f32_e32 v14, v63, v14
	v_pk_add_f32 v[56:57], v[56:57], v[52:53] op_sel_hi:[1,0] neg_lo:[0,1] neg_hi:[0,1]
	v_add_f32_e32 v14, v64, v14
	v_pk_mul_f32 v[66:67], v[56:57], v[56:57]
	v_add_f32_e32 v14, v65, v14
	v_pk_add_f32 v[58:59], v[58:59], v[52:53] op_sel_hi:[1,0] neg_lo:[0,1] neg_hi:[0,1]
	v_add_f32_e32 v14, v66, v14
	v_pk_mul_f32 v[68:69], v[58:59], v[58:59]
	v_add_f32_e32 v14, v67, v14
	v_pk_add_f32 v[48:49], v[48:49], v[52:53] op_sel_hi:[1,0] neg_lo:[0,1] neg_hi:[0,1]
	v_add_f32_e32 v14, v68, v14
	v_pk_mul_f32 v[70:71], v[48:49], v[48:49]
	v_add_f32_e32 v14, v69, v14
	v_pk_add_f32 v[50:51], v[50:51], v[52:53] op_sel_hi:[1,0] neg_lo:[0,1] neg_hi:[0,1]
	v_add_f32_e32 v14, v70, v14
	v_pk_mul_f32 v[52:53], v[50:51], v[50:51]
	v_add_f32_e32 v14, v71, v14
	v_add_f32_e32 v14, v52, v14
	v_add_f32_e32 v14, v53, v14
	ds_bpermute_b32 v15, v215, v14
	s_waitcnt lgkmcnt(0)
	v_add_f32_e32 v14, v14, v15
	ds_bpermute_b32 v15, v214, v14
	s_waitcnt lgkmcnt(0)
	v_add_f32_e32 v14, v14, v15
	s_waitcnt lgkmcnt(0)
	s_nop 1
	v_add_f32_dpp v14, v14, v14 row_ror:8 row_mask:0xf bank_mask:0xf
	s_waitcnt lgkmcnt(0)
	s_nop 1
	v_mov_b32_dpp v15, v14 row_half_mirror row_mask:0xf bank_mask:0xf
	s_nop 1
	v_add_f32_dpp v14, v15, v14 quad_perm:[3,2,1,0] row_mask:0xf bank_mask:0xf
	s_waitcnt lgkmcnt(0)
	s_nop 1
	v_add_f32_dpp v14, v14, v14 quad_perm:[2,3,0,1] row_mask:0xf bank_mask:0xf
	s_waitcnt lgkmcnt(0)
	s_nop 1
	v_add_f32_dpp v14, v14, v14 quad_perm:[1,0,3,2] row_mask:0xf bank_mask:0xf
	v_fmamk_f32 v14, v14, 0x3a800000, v201
	v_cmp_gt_f32_e32 vcc, s62, v14
	v_mul_f32_e32 v15, 0x4b800000, v14
	s_nop 0
	v_cndmask_b32_e32 v14, v14, v15, vcc
	v_rsq_f32_e32 v14, v14
	s_nop 0
	v_mul_f32_e32 v15, 0x45800000, v14
	v_cndmask_b32_e32 v52, v14, v15, vcc
	v_pk_mul_f32 v[14:15], v[16:17], v[52:53] op_sel_hi:[1,0]
	s_and_b64 vcc, exec, s[30:31]
	v_pk_fma_f32 v[14:15], v[2:3], v[14:15], v[6:7]
	v_pk_mul_f32 v[2:3], v[60:61], v[52:53] op_sel_hi:[1,0]
	s_nop 0
	v_pk_fma_f32 v[16:17], v[4:5], v[2:3], v[8:9]
	v_pk_mul_f32 v[2:3], v[44:45], v[52:53] op_sel_hi:[1,0]
	v_pk_mul_f32 v[4:5], v[50:51], v[52:53] op_sel_hi:[1,0]
	v_pk_fma_f32 v[10:11], v[10:11], v[2:3], v[18:19]
	v_pk_mul_f32 v[2:3], v[42:43], v[52:53] op_sel_hi:[1,0]
	s_waitcnt vmcnt(0)
	v_pk_fma_f32 v[4:5], v[32:33], v[4:5], v[36:37]
	v_pk_fma_f32 v[12:13], v[12:13], v[2:3], v[20:21]
	v_pk_mul_f32 v[2:3], v[56:57], v[52:53] op_sel_hi:[1,0]
	s_nop 0
	v_pk_fma_f32 v[6:7], v[22:23], v[2:3], v[26:27]
	v_pk_mul_f32 v[2:3], v[58:59], v[52:53] op_sel_hi:[1,0]
	s_nop 0
	v_pk_fma_f32 v[8:9], v[24:25], v[2:3], v[28:29]
	v_pk_mul_f32 v[2:3], v[48:49], v[52:53] op_sel_hi:[1,0]
	s_nop 0
	v_pk_fma_f32 v[2:3], v[30:31], v[2:3], v[34:35]
	s_cbranch_vccz .LBB0_873
	v_add_f32_e32 v18, 0, v14
	v_add_f32_e32 v18, v15, v18
	v_add_f32_e32 v18, v16, v18
	v_add_f32_e32 v18, v17, v18
	v_add_f32_e32 v18, v10, v18
	v_add_f32_e32 v18, v11, v18
	v_add_f32_e32 v18, v12, v18
	v_add_f32_e32 v18, v13, v18
	v_add_f32_e32 v18, v6, v18
	v_add_f32_e32 v18, v7, v18
	v_add_f32_e32 v18, v8, v18
	v_add_f32_e32 v18, v9, v18
	v_add_f32_e32 v18, v2, v18
	v_add_f32_e32 v18, v3, v18
	v_add_f32_e32 v18, v4, v18
	v_add_f32_e32 v18, v5, v18
	ds_bpermute_b32 v19, v215, v18
	v_add_u32_e32 v22, 3, v46
	global_store_dwordx4 v[40:41], v[14:17], off
	global_store_dwordx4 v[40:41], v[10:13], off offset:1024
	s_waitcnt lgkmcnt(0)
	v_add_f32_e32 v20, v18, v19
	ds_bpermute_b32 v21, v214, v20
	v_mov_b64_e32 v[18:19], s[16:17]
	v_mad_u64_u32 v[18:19], s[0:1], v22, s63, v[18:19]
	v_lshl_add_u64 v[48:49], v[18:19], 0, v[0:1]
	s_waitcnt lgkmcnt(0)
	v_add_f32_e32 v20, v20, v21
	v_add_co_u32_e32 v18, vcc, s58, v48
	s_mov_b64 s[0:1], 0x1000
	s_nop 0
	v_addc_co_u32_e32 v19, vcc, 0, v49, vcc
	s_waitcnt lgkmcnt(0)
	s_nop 1
	v_add_f32_dpp v0, v20, v20 row_ror:8 row_mask:0xf bank_mask:0xf
	v_lshl_add_u64 v[30:31], v[48:49], 0, s[0:1]
	global_load_dwordx4 v[18:21], v[18:19], off
	s_nop 0
	global_load_dwordx4 v[22:25], v[30:31], off offset:1024
	s_nop 0
	global_store_dwordx4 v[40:41], v[6:9], off offset:2048
	global_store_dwordx4 v[40:41], v[2:5], off offset:3072
	s_mov_b64 s[0:1], 0
	s_waitcnt lgkmcnt(0)
	s_nop 1
	v_mov_b32_dpp v26, v0 row_half_mirror row_mask:0xf bank_mask:0xf
	s_nop 1
	v_add_f32_dpp v0, v26, v0 quad_perm:[3,2,1,0] row_mask:0xf bank_mask:0xf
	s_waitcnt lgkmcnt(0)
	s_nop 1
	v_add_f32_dpp v0, v0, v0 quad_perm:[2,3,0,1] row_mask:0xf bank_mask:0xf
	global_load_dwordx4 v[26:29], v[30:31], off offset:2048
	s_nop 0
	global_load_dwordx4 v[30:33], v[30:31], off offset:3072
	s_nop 0
	global_load_dwordx4 v[34:37], v[48:49], off
	global_load_dwordx4 v[40:43], v[48:49], off offset:1024
	s_waitcnt lgkmcnt(0)
	s_nop 1
	v_add_f32_dpp v0, v0, v0 quad_perm:[1,0,3,2] row_mask:0xf bank_mask:0xf
	global_load_dwordx4 v[44:47], v[48:49], off offset:2048
	v_mul_f32_e32 v0, 0x3a800000, v0
	global_load_dwordx4 v[48:51], v[48:49], off offset:3072
	v_pk_add_f32 v[54:55], v[14:15], v[0:1] op_sel_hi:[1,0] neg_lo:[0,1] neg_hi:[0,1]
	v_pk_add_f32 v[52:53], v[16:17], v[0:1] op_sel_hi:[1,0] neg_lo:[0,1] neg_hi:[0,1]
	v_pk_mul_f32 v[60:61], v[54:55], v[54:55]
	v_pk_add_f32 v[56:57], v[12:13], v[0:1] op_sel_hi:[1,0] neg_lo:[0,1] neg_hi:[0,1]
	v_pk_mul_f32 v[58:59], v[52:53], v[52:53]
	v_pk_add_f32 v[64:65], v[10:11], v[0:1] op_sel_hi:[1,0] neg_lo:[0,1] neg_hi:[0,1]
	v_pk_add_f32 v[68:69], v[8:9], v[0:1] op_sel_hi:[1,0] neg_lo:[0,1] neg_hi:[0,1]
	v_pk_add_f32 v[72:73], v[6:7], v[0:1] op_sel_hi:[1,0] neg_lo:[0,1] neg_hi:[0,1]
	v_pk_add_f32 v[76:77], v[4:5], v[0:1] op_sel_hi:[1,0] neg_lo:[0,1] neg_hi:[0,1]
	v_pk_add_f32 v[80:81], v[2:3], v[0:1] op_sel_hi:[1,0] neg_lo:[0,1] neg_hi:[0,1]
	v_add_f32_e32 v0, v60, v61
	v_add_f32_e32 v0, v58, v0
	v_pk_mul_f32 v[66:67], v[64:65], v[64:65]
	v_add_f32_e32 v0, v59, v0
	v_add_f32_e32 v0, v66, v0
	v_pk_mul_f32 v[62:63], v[56:57], v[56:57]
	v_add_f32_e32 v0, v67, v0
	v_add_f32_e32 v0, v62, v0
	v_pk_mul_f32 v[74:75], v[72:73], v[72:73]
	v_add_f32_e32 v0, v63, v0
	v_add_f32_e32 v0, v74, v0
	v_pk_mul_f32 v[70:71], v[68:69], v[68:69]
	v_add_f32_e32 v0, v75, v0
	v_add_f32_e32 v0, v70, v0
	v_pk_mul_f32 v[82:83], v[80:81], v[80:81]
	v_add_f32_e32 v0, v71, v0
	v_add_f32_e32 v0, v82, v0
	v_pk_mul_f32 v[78:79], v[76:77], v[76:77]
	v_add_f32_e32 v0, v83, v0
	v_add_f32_e32 v0, v78, v0
	v_add_f32_e32 v0, v79, v0
	ds_bpermute_b32 v58, v215, v0
	s_waitcnt lgkmcnt(0)
	v_add_f32_e32 v0, v0, v58
	ds_bpermute_b32 v58, v214, v0
	s_waitcnt lgkmcnt(0)
	v_add_f32_e32 v0, v0, v58
	s_waitcnt lgkmcnt(0)
	s_nop 1
	v_add_f32_dpp v0, v0, v0 row_ror:8 row_mask:0xf bank_mask:0xf
	s_waitcnt lgkmcnt(0)
	s_nop 1
	v_mov_b32_dpp v58, v0 row_half_mirror row_mask:0xf bank_mask:0xf
	s_nop 1
	v_add_f32_dpp v0, v58, v0 quad_perm:[3,2,1,0] row_mask:0xf bank_mask:0xf
	s_waitcnt lgkmcnt(0)
	s_nop 1
	v_add_f32_dpp v0, v0, v0 quad_perm:[2,3,0,1] row_mask:0xf bank_mask:0xf
	s_waitcnt vmcnt(9)
	v_pk_add_f32 v[18:19], v[18:19], 1.0 op_sel_hi:[1,0]
	v_pk_add_f32 v[20:21], v[20:21], 1.0 op_sel_hi:[1,0]
	s_waitcnt vmcnt(8)
	v_pk_add_f32 v[22:23], v[22:23], 1.0 op_sel_hi:[1,0]
	v_pk_add_f32 v[24:25], v[24:25], 1.0 op_sel_hi:[1,0]
	s_waitcnt lgkmcnt(0)
	s_nop 1
	v_add_f32_dpp v0, v0, v0 quad_perm:[1,0,3,2] row_mask:0xf bank_mask:0xf
	v_fmamk_f32 v0, v0, 0x3a800000, v201
	v_mul_f32_e32 v58, 0x4b800000, v0
	v_cmp_gt_f32_e32 vcc, s62, v0
	s_waitcnt vmcnt(5)
	v_pk_add_f32 v[28:29], v[28:29], 1.0 op_sel_hi:[1,0]
	s_waitcnt vmcnt(4)
	v_pk_add_f32 v[30:31], v[30:31], 1.0 op_sel_hi:[1,0]
	v_cndmask_b32_e32 v0, v0, v58, vcc
	v_rsq_f32_e32 v0, v0
	v_pk_add_f32 v[32:33], v[32:33], 1.0 op_sel_hi:[1,0]
	v_pk_add_f32 v[26:27], v[26:27], 1.0 op_sel_hi:[1,0]
	v_mul_f32_e32 v58, 0x45800000, v0
	v_cndmask_b32_e32 v0, v0, v58, vcc
	v_pk_mul_f32 v[54:55], v[54:55], v[0:1] op_sel_hi:[1,0]
	v_pk_mul_f32 v[52:53], v[52:53], v[0:1] op_sel_hi:[1,0]
	s_waitcnt vmcnt(3)
	v_pk_fma_f32 v[18:19], v[18:19], v[54:55], v[34:35]
	v_pk_mul_f32 v[34:35], v[68:69], v[0:1] op_sel_hi:[1,0]
	v_pk_mul_f32 v[58:59], v[64:65], v[0:1] op_sel_hi:[1,0]
	s_waitcnt vmcnt(1)
	v_pk_fma_f32 v[28:29], v[34:35], v[28:29], v[46:47]
	v_pk_mul_f32 v[34:35], v[80:81], v[0:1] op_sel_hi:[1,0]
	v_pk_mul_f32 v[56:57], v[56:57], v[0:1] op_sel_hi:[1,0]
	v_pk_fma_f32 v[20:21], v[20:21], v[52:53], v[36:37]
	s_waitcnt vmcnt(0)
	v_pk_fma_f32 v[30:31], v[34:35], v[30:31], v[48:49]
	v_pk_mul_f32 v[34:35], v[76:77], v[0:1] op_sel_hi:[1,0]
	v_pk_mul_f32 v[60:61], v[72:73], v[0:1] op_sel_hi:[1,0]
	v_pk_fma_f32 v[22:23], v[22:23], v[58:59], v[40:41]
	v_pk_fma_f32 v[24:25], v[24:25], v[56:57], v[42:43]
	v_pk_fma_f32 v[32:33], v[34:35], v[32:33], v[50:51]
	v_lshl_add_u64 v[34:35], v[38:39], 1, v[138:139]
	v_cvt_pk_bf16_f32 v18, v18, v19
	v_cvt_pk_bf16_f32 v19, v20, v21
	v_pk_fma_f32 v[26:27], v[26:27], v[60:61], v[44:45]
	global_store_dwordx2 v[34:35], v[18:19], off
	v_cvt_pk_bf16_f32 v18, v22, v23
	v_cvt_pk_bf16_f32 v19, v24, v25
	global_store_dwordx2 v[34:35], v[18:19], off offset:512
	v_cvt_pk_bf16_f32 v18, v26, v27
	v_cvt_pk_bf16_f32 v19, v28, v29
	global_store_dwordx2 v[34:35], v[18:19], off offset:1024
	v_cvt_pk_bf16_f32 v18, v30, v31
	v_cvt_pk_bf16_f32 v19, v32, v33
	global_store_dwordx2 v[34:35], v[18:19], off offset:1536
